# GEMM K-loops: the mid-cluster s_setprio 0 / s_setprio 1 toggle between the two 16-MFMA halves removed (one priority raise per MFMA section)
# baseline (speedup 1.0000x reference)
.LBB0_157:
	ds_read_b128 v[154:157], v151
	ds_read_b128 v[158:161], v151 offset:1024
	ds_read_b128 v[162:165], v151 offset:2048
	ds_read_b128 v[166:169], v151 offset:3072
	ds_read_b128 v[170:173], v152
	ds_read_b128 v[174:177], v152 offset:1024
	ds_read_b128 v[178:181], v152 offset:2048
	ds_read_b128 v[182:185], v152 offset:3072
	s_add_u32 s8, s26, 0xfffc0080
	s_addc_u32 s9, s27, -1
	s_cmp_eq_u32 s45, 12
	s_cselect_b32 s29, s13, s9
	s_cselect_b32 s28, s39, s8
	s_cselect_b32 s9, s11, s44
	s_cselect_b32 s8, s40, s41
	v_lshl_add_u64 v[144:145], s[26:27], 0, v[136:137]
	s_add_i32 m0, s16, 0xc000
	ds_read_b128 v[186:189], v153
	ds_read_b128 v[190:193], v153 offset:1024
	ds_read_b128 v[196:199], v153 offset:2048
	ds_read_b128 v[200:203], v153 offset:3072
	ds_read_b128 v[204:207], v153 offset:4096
	ds_read_b128 v[208:211], v153 offset:5120
	ds_read_b128 v[212:215], v153 offset:6144
	ds_read_b128 v[216:219], v153 offset:7168
	global_load_lds_dwordx4 v[144:145], off
	v_lshl_add_u64 v[144:145], s[26:27], 0, v[138:139]
	s_add_i32 m0, s16, 0xe000
	s_nop 0
	global_load_lds_dwordx4 v[144:145], off
	s_waitcnt vmcnt(8)
	s_waitcnt lgkmcnt(0)
	s_barrier
	s_setprio 1
	s_waitcnt lgkmcnt(0)
	v_mfma_f32_16x16x32_bf16 v[124:127], v[154:157], v[186:189], v[124:127]
	v_mfma_f32_16x16x32_bf16 v[120:123], v[162:165], v[186:189], v[120:123]
	v_mfma_f32_16x16x32_bf16 v[116:119], v[154:157], v[196:199], v[116:119]
	v_mfma_f32_16x16x32_bf16 v[108:111], v[162:165], v[196:199], v[108:111]
	v_mfma_f32_16x16x32_bf16 v[96:99], v[154:157], v[204:207], v[96:99]
	v_mfma_f32_16x16x32_bf16 v[88:91], v[162:165], v[204:207], v[88:91]
	v_mfma_f32_16x16x32_bf16 v[84:87], v[154:157], v[212:215], v[84:87]
	v_mfma_f32_16x16x32_bf16 v[76:79], v[162:165], v[212:215], v[76:79]
	v_mfma_f32_16x16x32_bf16 v[124:127], v[158:161], v[190:193], v[124:127]
	v_mfma_f32_16x16x32_bf16 v[120:123], v[166:169], v[190:193], v[120:123]
	v_mfma_f32_16x16x32_bf16 v[116:119], v[158:161], v[200:203], v[116:119]
	v_mfma_f32_16x16x32_bf16 v[108:111], v[166:169], v[200:203], v[108:111]
	v_mfma_f32_16x16x32_bf16 v[96:99], v[158:161], v[208:211], v[96:99]
	v_mfma_f32_16x16x32_bf16 v[88:91], v[166:169], v[208:211], v[88:91]
	v_mfma_f32_16x16x32_bf16 v[84:87], v[158:161], v[216:219], v[84:87]
	v_mfma_f32_16x16x32_bf16 v[76:79], v[166:169], v[216:219], v[76:79]
	v_mfma_f32_16x16x32_bf16 v[112:115], v[170:173], v[186:189], v[112:115]
	v_mfma_f32_16x16x32_bf16 v[104:107], v[178:181], v[186:189], v[104:107]
	v_mfma_f32_16x16x32_bf16 v[100:103], v[170:173], v[196:199], v[100:103]
	v_mfma_f32_16x16x32_bf16 v[92:95], v[178:181], v[196:199], v[92:95]
	v_mfma_f32_16x16x32_bf16 v[80:83], v[170:173], v[204:207], v[80:83]
	v_mfma_f32_16x16x32_bf16 v[72:75], v[178:181], v[204:207], v[72:75]
	v_mfma_f32_16x16x32_bf16 v[68:71], v[170:173], v[212:215], v[68:71]
	v_mfma_f32_16x16x32_bf16 v[64:67], v[178:181], v[212:215], v[64:67]
	v_mfma_f32_16x16x32_bf16 v[112:115], v[174:177], v[190:193], v[112:115]
	v_mfma_f32_16x16x32_bf16 v[104:107], v[182:185], v[190:193], v[104:107]
	v_mfma_f32_16x16x32_bf16 v[100:103], v[174:177], v[200:203], v[100:103]
	v_mfma_f32_16x16x32_bf16 v[92:95], v[182:185], v[200:203], v[92:95]
	v_mfma_f32_16x16x32_bf16 v[80:83], v[174:177], v[208:211], v[80:83]
	v_mfma_f32_16x16x32_bf16 v[72:75], v[182:185], v[208:211], v[72:75]
	v_mfma_f32_16x16x32_bf16 v[68:71], v[174:177], v[216:219], v[68:71]
	v_mfma_f32_16x16x32_bf16 v[64:67], v[182:185], v[216:219], v[64:67]
	s_setprio 0
	s_barrier
	s_add_i32 s46, s31, s3
	v_lshl_add_u64 v[144:145], s[8:9], 0, v[132:133]
	s_mov_b32 m0, s46
	ds_read_b128 v[186:189], v153 offset:16384
	ds_read_b128 v[190:193], v153 offset:17408
	ds_read_b128 v[196:199], v153 offset:18432
	ds_read_b128 v[200:203], v153 offset:19456
	ds_read_b128 v[204:207], v153 offset:20480
	ds_read_b128 v[208:211], v153 offset:21504
	ds_read_b128 v[212:215], v153 offset:22528
	ds_read_b128 v[216:219], v153 offset:23552
	global_load_lds_dwordx4 v[144:145], off
	s_add_i32 m0, s46, 0x2000
	s_add_u32 s46, s8, 0x40000
	v_lshl_add_u64 v[220:221], s[8:9], 0, v[128:129]
	s_addc_u32 s47, s9, 0
	s_add_i32 s48, s33, s3
	global_load_lds_dwordx4 v[220:221], off
	v_lshl_add_u64 v[222:223], s[46:47], 0, v[132:133]
	s_mov_b32 m0, s48
	v_lshl_add_u64 v[224:225], s[28:29], 0, v[130:131]
	global_load_lds_dwordx4 v[222:223], off
	v_lshl_add_u64 v[222:223], s[46:47], 0, v[128:129]
	s_add_i32 m0, s48, 0x2000
	s_nop 0
	global_load_lds_dwordx4 v[222:223], off
	v_lshl_add_u64 v[222:223], s[28:29], 0, v[134:135]
	s_mov_b32 m0, s16
	s_nop 0
	global_load_lds_dwordx4 v[222:223], off
	s_mov_b32 m0, s17
	s_nop 0
	global_load_lds_dwordx4 v[224:225], off
	s_waitcnt vmcnt(8)
	s_waitcnt lgkmcnt(0)
	s_barrier
	s_setprio 1
	s_waitcnt lgkmcnt(0)
	v_mfma_f32_16x16x32_bf16 v[60:63], v[154:157], v[186:189], v[60:63]
	v_mfma_f32_16x16x32_bf16 v[56:59], v[162:165], v[186:189], v[56:59]
	v_mfma_f32_16x16x32_bf16 v[52:55], v[154:157], v[196:199], v[52:55]
	v_mfma_f32_16x16x32_bf16 v[44:47], v[162:165], v[196:199], v[44:47]
	v_mfma_f32_16x16x32_bf16 v[32:35], v[154:157], v[204:207], v[32:35]
	v_mfma_f32_16x16x32_bf16 v[24:27], v[162:165], v[204:207], v[24:27]
	v_mfma_f32_16x16x32_bf16 v[20:23], v[154:157], v[212:215], v[20:23]
	v_mfma_f32_16x16x32_bf16 v[12:15], v[162:165], v[212:215], v[12:15]
	v_mfma_f32_16x16x32_bf16 v[60:63], v[158:161], v[190:193], v[60:63]
	v_mfma_f32_16x16x32_bf16 v[56:59], v[166:169], v[190:193], v[56:59]
	v_mfma_f32_16x16x32_bf16 v[52:55], v[158:161], v[200:203], v[52:55]
	v_mfma_f32_16x16x32_bf16 v[44:47], v[166:169], v[200:203], v[44:47]
	v_mfma_f32_16x16x32_bf16 v[32:35], v[158:161], v[208:211], v[32:35]
	v_mfma_f32_16x16x32_bf16 v[24:27], v[166:169], v[208:211], v[24:27]
	v_mfma_f32_16x16x32_bf16 v[20:23], v[158:161], v[216:219], v[20:23]
	v_mfma_f32_16x16x32_bf16 v[12:15], v[166:169], v[216:219], v[12:15]
	v_mfma_f32_16x16x32_bf16 v[48:51], v[170:173], v[186:189], v[48:51]
	v_mfma_f32_16x16x32_bf16 v[40:43], v[178:181], v[186:189], v[40:43]
	v_mfma_f32_16x16x32_bf16 v[36:39], v[170:173], v[196:199], v[36:39]
	v_mfma_f32_16x16x32_bf16 v[28:31], v[178:181], v[196:199], v[28:31]
	v_mfma_f32_16x16x32_bf16 v[16:19], v[170:173], v[204:207], v[16:19]
	v_mfma_f32_16x16x32_bf16 v[8:11], v[178:181], v[204:207], v[8:11]
	v_mfma_f32_16x16x32_bf16 v[4:7], v[170:173], v[212:215], v[4:7]
	v_mfma_f32_16x16x32_bf16 v[0:3], v[178:181], v[212:215], v[0:3]
	v_mfma_f32_16x16x32_bf16 v[48:51], v[174:177], v[190:193], v[48:51]
	v_mfma_f32_16x16x32_bf16 v[40:43], v[182:185], v[190:193], v[40:43]
	v_mfma_f32_16x16x32_bf16 v[36:39], v[174:177], v[200:203], v[36:39]
	v_mfma_f32_16x16x32_bf16 v[28:31], v[182:185], v[200:203], v[28:31]
	v_mfma_f32_16x16x32_bf16 v[16:19], v[174:177], v[208:211], v[16:19]
	v_mfma_f32_16x16x32_bf16 v[8:11], v[182:185], v[208:211], v[8:11]
	v_mfma_f32_16x16x32_bf16 v[4:7], v[174:177], v[216:219], v[4:7]
	v_mfma_f32_16x16x32_bf16 v[0:3], v[182:185], v[216:219], v[0:3]
	s_setprio 0
	s_barrier
	s_add_i32 s46, 0, 0x18000
	s_add_i32 s47, 0, 0x1c000
	v_add_u32_e32 v166, s46, v148
	v_add_u32_e32 v182, s47, v148
	ds_read_b128 v[154:157], v166
	ds_read_b128 v[158:161], v166 offset:1024
	ds_read_b128 v[162:165], v166 offset:2048
	ds_read_b128 v[166:169], v166 offset:3072
	ds_read_b128 v[170:173], v182
	ds_read_b128 v[174:177], v182 offset:1024
	ds_read_b128 v[178:181], v182 offset:2048
	ds_read_b128 v[182:185], v182 offset:3072
	s_add_u32 s28, s28, 0x40000
	s_addc_u32 s29, s29, 0
	s_mov_b32 m0, s18
	v_lshl_add_u64 v[226:227], s[28:29], 0, v[134:135]
	ds_read_b128 v[186:189], v153 offset:32768
	ds_read_b128 v[190:193], v153 offset:33792
	ds_read_b128 v[196:199], v153 offset:34816
	ds_read_b128 v[200:203], v153 offset:35840
	ds_read_b128 v[204:207], v153 offset:36864
	ds_read_b128 v[208:211], v153 offset:37888
	ds_read_b128 v[212:215], v153 offset:38912
	ds_read_b128 v[216:219], v153 offset:39936
	global_load_lds_dwordx4 v[226:227], off
	v_lshl_add_u64 v[226:227], s[28:29], 0, v[130:131]
	s_mov_b32 m0, s19
	s_nop 0
	global_load_lds_dwordx4 v[226:227], off
	s_waitcnt vmcnt(8)
	s_waitcnt lgkmcnt(0)
	s_barrier
	s_setprio 1
	s_waitcnt lgkmcnt(0)
	v_mfma_f32_16x16x32_bf16 v[124:127], v[154:157], v[186:189], v[124:127]
	v_mfma_f32_16x16x32_bf16 v[120:123], v[162:165], v[186:189], v[120:123]
	v_mfma_f32_16x16x32_bf16 v[116:119], v[154:157], v[196:199], v[116:119]
	v_mfma_f32_16x16x32_bf16 v[108:111], v[162:165], v[196:199], v[108:111]
	v_mfma_f32_16x16x32_bf16 v[96:99], v[154:157], v[204:207], v[96:99]
	v_mfma_f32_16x16x32_bf16 v[88:91], v[162:165], v[204:207], v[88:91]
	v_mfma_f32_16x16x32_bf16 v[84:87], v[154:157], v[212:215], v[84:87]
	v_mfma_f32_16x16x32_bf16 v[76:79], v[162:165], v[212:215], v[76:79]
	v_mfma_f32_16x16x32_bf16 v[124:127], v[158:161], v[190:193], v[124:127]
	v_mfma_f32_16x16x32_bf16 v[120:123], v[166:169], v[190:193], v[120:123]
	v_mfma_f32_16x16x32_bf16 v[116:119], v[158:161], v[200:203], v[116:119]
	v_mfma_f32_16x16x32_bf16 v[108:111], v[166:169], v[200:203], v[108:111]
	v_mfma_f32_16x16x32_bf16 v[96:99], v[158:161], v[208:211], v[96:99]
	v_mfma_f32_16x16x32_bf16 v[88:91], v[166:169], v[208:211], v[88:91]
	v_mfma_f32_16x16x32_bf16 v[84:87], v[158:161], v[216:219], v[84:87]
	v_mfma_f32_16x16x32_bf16 v[76:79], v[166:169], v[216:219], v[76:79]
	v_mfma_f32_16x16x32_bf16 v[112:115], v[170:173], v[186:189], v[112:115]
	v_mfma_f32_16x16x32_bf16 v[104:107], v[178:181], v[186:189], v[104:107]
	v_mfma_f32_16x16x32_bf16 v[100:103], v[170:173], v[196:199], v[100:103]
	v_mfma_f32_16x16x32_bf16 v[92:95], v[178:181], v[196:199], v[92:95]
	v_mfma_f32_16x16x32_bf16 v[80:83], v[170:173], v[204:207], v[80:83]
	v_mfma_f32_16x16x32_bf16 v[72:75], v[178:181], v[204:207], v[72:75]
	v_mfma_f32_16x16x32_bf16 v[68:71], v[170:173], v[212:215], v[68:71]
	v_mfma_f32_16x16x32_bf16 v[64:67], v[178:181], v[212:215], v[64:67]
	v_mfma_f32_16x16x32_bf16 v[112:115], v[174:177], v[190:193], v[112:115]
	v_mfma_f32_16x16x32_bf16 v[104:107], v[182:185], v[190:193], v[104:107]
	v_mfma_f32_16x16x32_bf16 v[100:103], v[174:177], v[200:203], v[100:103]
	v_mfma_f32_16x16x32_bf16 v[92:95], v[182:185], v[200:203], v[92:95]
	v_mfma_f32_16x16x32_bf16 v[80:83], v[174:177], v[208:211], v[80:83]
	v_mfma_f32_16x16x32_bf16 v[72:75], v[182:185], v[208:211], v[72:75]
	v_mfma_f32_16x16x32_bf16 v[68:71], v[174:177], v[216:219], v[68:71]
	v_mfma_f32_16x16x32_bf16 v[64:67], v[182:185], v[216:219], v[64:67]
	s_setprio 0
	s_barrier
	s_add_i32 s28, s46, s3
	v_lshl_add_u64 v[144:145], v[144:145], 0, s[4:5]
	s_mov_b32 m0, s28
	ds_read_b128 v[186:189], v153 offset:49152
	ds_read_b128 v[190:193], v153 offset:50176
	ds_read_b128 v[196:199], v153 offset:51200
	ds_read_b128 v[200:203], v153 offset:52224
	ds_read_b128 v[204:207], v153 offset:53248
	ds_read_b128 v[208:211], v153 offset:54272
	ds_read_b128 v[212:215], v153 offset:55296
	ds_read_b128 v[216:219], v153 offset:56320
	global_load_lds_dwordx4 v[144:145], off
	s_add_i32 m0, s28, 0x2000
	s_add_u32 s8, s8, 0x40080
	v_lshl_add_u64 v[144:145], v[220:221], 0, s[4:5]
	s_addc_u32 s9, s9, 0
	s_add_i32 s28, s47, s3
	global_load_lds_dwordx4 v[144:145], off
	v_lshl_add_u64 v[144:145], s[8:9], 0, v[132:133]
	s_mov_b32 m0, s28
	s_nop 0
	global_load_lds_dwordx4 v[144:145], off
	v_lshl_add_u64 v[144:145], s[8:9], 0, v[128:129]
	s_add_i32 m0, s28, 0x2000
	s_nop 0
	global_load_lds_dwordx4 v[144:145], off
	v_lshl_add_u64 v[144:145], v[222:223], 0, s[4:5]
	s_mov_b32 m0, s25
	s_nop 0
	global_load_lds_dwordx4 v[144:145], off
	v_lshl_add_u64 v[144:145], v[224:225], 0, s[4:5]
	s_mov_b32 m0, s30
	s_nop 0
	global_load_lds_dwordx4 v[144:145], off
	s_waitcnt vmcnt(8)
	s_waitcnt lgkmcnt(0)
	s_barrier
	s_setprio 1
	s_waitcnt lgkmcnt(0)
	v_mfma_f32_16x16x32_bf16 v[60:63], v[154:157], v[186:189], v[60:63]
	v_mfma_f32_16x16x32_bf16 v[56:59], v[162:165], v[186:189], v[56:59]
	v_mfma_f32_16x16x32_bf16 v[52:55], v[154:157], v[196:199], v[52:55]
	v_mfma_f32_16x16x32_bf16 v[44:47], v[162:165], v[196:199], v[44:47]
	v_mfma_f32_16x16x32_bf16 v[32:35], v[154:157], v[204:207], v[32:35]
	v_mfma_f32_16x16x32_bf16 v[24:27], v[162:165], v[204:207], v[24:27]
	v_mfma_f32_16x16x32_bf16 v[20:23], v[154:157], v[212:215], v[20:23]
	v_mfma_f32_16x16x32_bf16 v[12:15], v[162:165], v[212:215], v[12:15]
	v_mfma_f32_16x16x32_bf16 v[60:63], v[158:161], v[190:193], v[60:63]
	v_mfma_f32_16x16x32_bf16 v[56:59], v[166:169], v[190:193], v[56:59]
	v_mfma_f32_16x16x32_bf16 v[52:55], v[158:161], v[200:203], v[52:55]
	v_mfma_f32_16x16x32_bf16 v[44:47], v[166:169], v[200:203], v[44:47]
	v_mfma_f32_16x16x32_bf16 v[32:35], v[158:161], v[208:211], v[32:35]
	v_mfma_f32_16x16x32_bf16 v[24:27], v[166:169], v[208:211], v[24:27]
	v_mfma_f32_16x16x32_bf16 v[20:23], v[158:161], v[216:219], v[20:23]
	v_mfma_f32_16x16x32_bf16 v[12:15], v[166:169], v[216:219], v[12:15]
	v_mfma_f32_16x16x32_bf16 v[48:51], v[170:173], v[186:189], v[48:51]
	v_mfma_f32_16x16x32_bf16 v[40:43], v[178:181], v[186:189], v[40:43]
	v_mfma_f32_16x16x32_bf16 v[36:39], v[170:173], v[196:199], v[36:39]
	v_mfma_f32_16x16x32_bf16 v[28:31], v[178:181], v[196:199], v[28:31]
	v_mfma_f32_16x16x32_bf16 v[16:19], v[170:173], v[204:207], v[16:19]
	v_mfma_f32_16x16x32_bf16 v[8:11], v[178:181], v[204:207], v[8:11]
	v_mfma_f32_16x16x32_bf16 v[4:7], v[170:173], v[212:215], v[4:7]
	v_mfma_f32_16x16x32_bf16 v[0:3], v[178:181], v[212:215], v[0:3]
	v_mfma_f32_16x16x32_bf16 v[48:51], v[174:177], v[190:193], v[48:51]
	v_mfma_f32_16x16x32_bf16 v[40:43], v[182:185], v[190:193], v[40:43]
	v_mfma_f32_16x16x32_bf16 v[36:39], v[174:177], v[200:203], v[36:39]
	v_mfma_f32_16x16x32_bf16 v[28:31], v[182:185], v[200:203], v[28:31]
	v_mfma_f32_16x16x32_bf16 v[16:19], v[174:177], v[208:211], v[16:19]
	v_mfma_f32_16x16x32_bf16 v[8:11], v[182:185], v[208:211], v[8:11]
	v_mfma_f32_16x16x32_bf16 v[4:7], v[174:177], v[216:219], v[4:7]
	v_mfma_f32_16x16x32_bf16 v[0:3], v[182:185], v[216:219], v[0:3]
	s_setprio 0
	s_barrier
	s_add_i32 s45, s45, 2
	s_add_u32 s26, s26, 0x100
	s_addc_u32 s27, s27, 0
	s_add_u32 s41, s41, 0x100
	s_addc_u32 s44, s44, 0
	s_cmp_gt_u32 s45, 13
	s_cbranch_scc0 .LBB0_157
	s_and_b64 vcc, exec, s[6:7]
	s_cbranch_vccz .LBB0_160
	s_barrier

.LBB0_666:
	ds_read_b128 v[144:147], v153
	ds_read_b128 v[162:165], v153 offset:1024
	ds_read_b128 v[166:169], v153 offset:2048
	ds_read_b128 v[170:173], v153 offset:3072
	ds_read_b128 v[174:177], v154
	ds_read_b128 v[178:181], v154 offset:1024
	ds_read_b128 v[182:185], v154 offset:2048
	ds_read_b128 v[186:189], v154 offset:3072
	s_add_u32 s8, s38, 0xfffc0080
	s_addc_u32 s9, s39, -1
	s_cmp_eq_u32 s65, 12
	s_cselect_b32 s41, s27, s9
	s_cselect_b32 s40, s37, s8
	s_cselect_b32 s9, s25, s64
	s_cselect_b32 s8, s60, s61
	v_lshl_add_u64 v[156:157], s[38:39], 0, v[136:137]
	s_add_i32 m0, s4, 0xc000
	ds_read_b128 v[190:193], v155
	ds_read_b128 v[198:201], v155 offset:1024
	ds_read_b128 v[202:205], v155 offset:2048
	ds_read_b128 v[206:209], v155 offset:3072
	ds_read_b128 v[210:213], v155 offset:4096
	ds_read_b128 v[214:217], v155 offset:5120
	ds_read_b128 v[218:221], v155 offset:6144
	ds_read_b128 v[222:225], v155 offset:7168
	global_load_lds_dwordx4 v[156:157], off
	v_lshl_add_u64 v[156:157], s[38:39], 0, v[138:139]
	s_add_i32 m0, s4, 0xe000
	s_nop 0
	global_load_lds_dwordx4 v[156:157], off
	s_waitcnt vmcnt(8)
	s_waitcnt lgkmcnt(0)
	s_barrier
	s_setprio 1
	s_waitcnt lgkmcnt(0)
	v_mfma_f32_16x16x32_bf16 v[124:127], v[144:147], v[190:193], v[124:127]
	v_mfma_f32_16x16x32_bf16 v[120:123], v[166:169], v[190:193], v[120:123]
	v_mfma_f32_16x16x32_bf16 v[108:111], v[144:147], v[202:205], v[108:111]
	v_mfma_f32_16x16x32_bf16 v[104:107], v[166:169], v[202:205], v[104:107]
	v_mfma_f32_16x16x32_bf16 v[92:95], v[144:147], v[210:213], v[92:95]
	v_mfma_f32_16x16x32_bf16 v[88:91], v[166:169], v[210:213], v[88:91]
	v_mfma_f32_16x16x32_bf16 v[76:79], v[144:147], v[218:221], v[76:79]
	v_mfma_f32_16x16x32_bf16 v[72:75], v[166:169], v[218:221], v[72:75]
	v_mfma_f32_16x16x32_bf16 v[124:127], v[162:165], v[198:201], v[124:127]
	v_mfma_f32_16x16x32_bf16 v[120:123], v[170:173], v[198:201], v[120:123]
	v_mfma_f32_16x16x32_bf16 v[108:111], v[162:165], v[206:209], v[108:111]
	v_mfma_f32_16x16x32_bf16 v[104:107], v[170:173], v[206:209], v[104:107]
	v_mfma_f32_16x16x32_bf16 v[92:95], v[162:165], v[214:217], v[92:95]
	v_mfma_f32_16x16x32_bf16 v[88:91], v[170:173], v[214:217], v[88:91]
	v_mfma_f32_16x16x32_bf16 v[76:79], v[162:165], v[222:225], v[76:79]
	v_mfma_f32_16x16x32_bf16 v[72:75], v[170:173], v[222:225], v[72:75]
	v_mfma_f32_16x16x32_bf16 v[116:119], v[174:177], v[190:193], v[116:119]
	v_mfma_f32_16x16x32_bf16 v[112:115], v[182:185], v[190:193], v[112:115]
	v_mfma_f32_16x16x32_bf16 v[100:103], v[174:177], v[202:205], v[100:103]
	v_mfma_f32_16x16x32_bf16 v[96:99], v[182:185], v[202:205], v[96:99]
	v_mfma_f32_16x16x32_bf16 v[84:87], v[174:177], v[210:213], v[84:87]
	v_mfma_f32_16x16x32_bf16 v[80:83], v[182:185], v[210:213], v[80:83]
	v_mfma_f32_16x16x32_bf16 v[68:71], v[174:177], v[218:221], v[68:71]
	v_mfma_f32_16x16x32_bf16 v[64:67], v[182:185], v[218:221], v[64:67]
	v_mfma_f32_16x16x32_bf16 v[116:119], v[178:181], v[198:201], v[116:119]
	v_mfma_f32_16x16x32_bf16 v[112:115], v[186:189], v[198:201], v[112:115]
	v_mfma_f32_16x16x32_bf16 v[100:103], v[178:181], v[206:209], v[100:103]
	v_mfma_f32_16x16x32_bf16 v[96:99], v[186:189], v[206:209], v[96:99]
	v_mfma_f32_16x16x32_bf16 v[84:87], v[178:181], v[214:217], v[84:87]
	v_mfma_f32_16x16x32_bf16 v[80:83], v[186:189], v[214:217], v[80:83]
	v_mfma_f32_16x16x32_bf16 v[68:71], v[178:181], v[222:225], v[68:71]
	v_mfma_f32_16x16x32_bf16 v[64:67], v[186:189], v[222:225], v[64:67]
	s_setprio 0
	s_barrier
	s_add_i32 s66, s55, s3
	v_lshl_add_u64 v[156:157], s[8:9], 0, v[130:131]
	s_mov_b32 m0, s66
	ds_read_b128 v[190:193], v155 offset:16384
	ds_read_b128 v[198:201], v155 offset:17408
	ds_read_b128 v[202:205], v155 offset:18432
	ds_read_b128 v[206:209], v155 offset:19456
	ds_read_b128 v[210:213], v155 offset:20480
	ds_read_b128 v[214:217], v155 offset:21504
	ds_read_b128 v[218:221], v155 offset:22528
	ds_read_b128 v[222:225], v155 offset:23552
	global_load_lds_dwordx4 v[156:157], off
	s_add_i32 m0, s66, 0x2000
	s_add_u32 s66, s8, 0x40000
	v_lshl_add_u64 v[226:227], s[8:9], 0, v[134:135]
	s_addc_u32 s67, s9, 0
	s_add_i32 s73, s58, s3
	global_load_lds_dwordx4 v[226:227], off
	v_lshl_add_u64 v[228:229], s[66:67], 0, v[130:131]
	s_mov_b32 m0, s73
	v_lshl_add_u64 v[230:231], s[40:41], 0, v[132:133]
	global_load_lds_dwordx4 v[228:229], off
	v_lshl_add_u64 v[228:229], s[66:67], 0, v[134:135]
	s_add_i32 m0, s73, 0x2000
	s_nop 0
	global_load_lds_dwordx4 v[228:229], off
	v_lshl_add_u64 v[228:229], s[40:41], 0, v[128:129]
	s_mov_b32 m0, s4
	s_nop 0
	global_load_lds_dwordx4 v[228:229], off
	s_mov_b32 m0, s5
	s_nop 0
	global_load_lds_dwordx4 v[230:231], off
	s_waitcnt vmcnt(8)
	s_waitcnt lgkmcnt(0)
	s_barrier
	s_setprio 1
	s_waitcnt lgkmcnt(0)
	v_mfma_f32_16x16x32_bf16 v[60:63], v[144:147], v[190:193], v[60:63]
	v_mfma_f32_16x16x32_bf16 v[56:59], v[166:169], v[190:193], v[56:59]
	v_mfma_f32_16x16x32_bf16 v[44:47], v[144:147], v[202:205], v[44:47]
	v_mfma_f32_16x16x32_bf16 v[40:43], v[166:169], v[202:205], v[40:43]
	v_mfma_f32_16x16x32_bf16 v[28:31], v[144:147], v[210:213], v[28:31]
	v_mfma_f32_16x16x32_bf16 v[24:27], v[166:169], v[210:213], v[24:27]
	v_mfma_f32_16x16x32_bf16 v[12:15], v[144:147], v[218:221], v[12:15]
	v_mfma_f32_16x16x32_bf16 v[8:11], v[166:169], v[218:221], v[8:11]
	v_mfma_f32_16x16x32_bf16 v[60:63], v[162:165], v[198:201], v[60:63]
	v_mfma_f32_16x16x32_bf16 v[56:59], v[170:173], v[198:201], v[56:59]
	v_mfma_f32_16x16x32_bf16 v[44:47], v[162:165], v[206:209], v[44:47]
	v_mfma_f32_16x16x32_bf16 v[40:43], v[170:173], v[206:209], v[40:43]
	v_mfma_f32_16x16x32_bf16 v[28:31], v[162:165], v[214:217], v[28:31]
	v_mfma_f32_16x16x32_bf16 v[24:27], v[170:173], v[214:217], v[24:27]
	v_mfma_f32_16x16x32_bf16 v[12:15], v[162:165], v[222:225], v[12:15]
	v_mfma_f32_16x16x32_bf16 v[8:11], v[170:173], v[222:225], v[8:11]
	v_mfma_f32_16x16x32_bf16 v[52:55], v[174:177], v[190:193], v[52:55]
	v_mfma_f32_16x16x32_bf16 v[48:51], v[182:185], v[190:193], v[48:51]
	v_mfma_f32_16x16x32_bf16 v[36:39], v[174:177], v[202:205], v[36:39]
	v_mfma_f32_16x16x32_bf16 v[32:35], v[182:185], v[202:205], v[32:35]
	v_mfma_f32_16x16x32_bf16 v[20:23], v[174:177], v[210:213], v[20:23]
	v_mfma_f32_16x16x32_bf16 v[16:19], v[182:185], v[210:213], v[16:19]
	v_mfma_f32_16x16x32_bf16 v[4:7], v[174:177], v[218:221], v[4:7]
	v_mfma_f32_16x16x32_bf16 v[0:3], v[182:185], v[218:221], v[0:3]
	v_mfma_f32_16x16x32_bf16 v[52:55], v[178:181], v[198:201], v[52:55]
	v_mfma_f32_16x16x32_bf16 v[48:51], v[186:189], v[198:201], v[48:51]
	v_mfma_f32_16x16x32_bf16 v[36:39], v[178:181], v[206:209], v[36:39]
	v_mfma_f32_16x16x32_bf16 v[32:35], v[186:189], v[206:209], v[32:35]
	v_mfma_f32_16x16x32_bf16 v[20:23], v[178:181], v[214:217], v[20:23]
	v_mfma_f32_16x16x32_bf16 v[16:19], v[186:189], v[214:217], v[16:19]
	v_mfma_f32_16x16x32_bf16 v[4:7], v[178:181], v[222:225], v[4:7]
	v_mfma_f32_16x16x32_bf16 v[0:3], v[186:189], v[222:225], v[0:3]
	s_setprio 0
	s_barrier
	s_add_i32 s66, 0, 0x18000
	v_add_u32_e32 v158, s66, v149
	s_add_i32 s67, 0, 0x1c000
	ds_read_b128 v[144:147], v158
	ds_read_b128 v[162:165], v158 offset:1024
	ds_read_b128 v[166:169], v158 offset:2048
	ds_read_b128 v[170:173], v158 offset:3072
	v_add_u32_e32 v158, s67, v149
	ds_read_b128 v[174:177], v158
	ds_read_b128 v[178:181], v158 offset:1024
	ds_read_b128 v[182:185], v158 offset:2048
	ds_read_b128 v[186:189], v158 offset:3072
	s_add_u32 s40, s40, 0x40000
	s_addc_u32 s41, s41, 0
	s_mov_b32 m0, s16
	v_lshl_add_u64 v[232:233], s[40:41], 0, v[128:129]
	ds_read_b128 v[190:193], v155 offset:32768
	ds_read_b128 v[198:201], v155 offset:33792
	ds_read_b128 v[202:205], v155 offset:34816
	ds_read_b128 v[206:209], v155 offset:35840
	ds_read_b128 v[210:213], v155 offset:36864
	ds_read_b128 v[214:217], v155 offset:37888
	ds_read_b128 v[218:221], v155 offset:38912
	ds_read_b128 v[222:225], v155 offset:39936
	global_load_lds_dwordx4 v[232:233], off
	v_lshl_add_u64 v[232:233], s[40:41], 0, v[132:133]
	s_mov_b32 m0, s17
	s_nop 0
	global_load_lds_dwordx4 v[232:233], off
	s_waitcnt vmcnt(8)
	s_waitcnt lgkmcnt(0)
	s_barrier
	s_setprio 1
	s_waitcnt lgkmcnt(0)
	v_mfma_f32_16x16x32_bf16 v[124:127], v[144:147], v[190:193], v[124:127]
	v_mfma_f32_16x16x32_bf16 v[120:123], v[166:169], v[190:193], v[120:123]
	v_mfma_f32_16x16x32_bf16 v[108:111], v[144:147], v[202:205], v[108:111]
	v_mfma_f32_16x16x32_bf16 v[104:107], v[166:169], v[202:205], v[104:107]
	v_mfma_f32_16x16x32_bf16 v[92:95], v[144:147], v[210:213], v[92:95]
	v_mfma_f32_16x16x32_bf16 v[88:91], v[166:169], v[210:213], v[88:91]
	v_mfma_f32_16x16x32_bf16 v[76:79], v[144:147], v[218:221], v[76:79]
	v_mfma_f32_16x16x32_bf16 v[72:75], v[166:169], v[218:221], v[72:75]
	v_mfma_f32_16x16x32_bf16 v[124:127], v[162:165], v[198:201], v[124:127]
	v_mfma_f32_16x16x32_bf16 v[120:123], v[170:173], v[198:201], v[120:123]
	v_mfma_f32_16x16x32_bf16 v[108:111], v[162:165], v[206:209], v[108:111]
	v_mfma_f32_16x16x32_bf16 v[104:107], v[170:173], v[206:209], v[104:107]
	v_mfma_f32_16x16x32_bf16 v[92:95], v[162:165], v[214:217], v[92:95]
	v_mfma_f32_16x16x32_bf16 v[88:91], v[170:173], v[214:217], v[88:91]
	v_mfma_f32_16x16x32_bf16 v[76:79], v[162:165], v[222:225], v[76:79]
	v_mfma_f32_16x16x32_bf16 v[72:75], v[170:173], v[222:225], v[72:75]
	v_mfma_f32_16x16x32_bf16 v[116:119], v[174:177], v[190:193], v[116:119]
	v_mfma_f32_16x16x32_bf16 v[112:115], v[182:185], v[190:193], v[112:115]
	v_mfma_f32_16x16x32_bf16 v[100:103], v[174:177], v[202:205], v[100:103]
	v_mfma_f32_16x16x32_bf16 v[96:99], v[182:185], v[202:205], v[96:99]
	v_mfma_f32_16x16x32_bf16 v[84:87], v[174:177], v[210:213], v[84:87]
	v_mfma_f32_16x16x32_bf16 v[80:83], v[182:185], v[210:213], v[80:83]
	v_mfma_f32_16x16x32_bf16 v[68:71], v[174:177], v[218:221], v[68:71]
	v_mfma_f32_16x16x32_bf16 v[64:67], v[182:185], v[218:221], v[64:67]
	v_mfma_f32_16x16x32_bf16 v[116:119], v[178:181], v[198:201], v[116:119]
	v_mfma_f32_16x16x32_bf16 v[112:115], v[186:189], v[198:201], v[112:115]
	v_mfma_f32_16x16x32_bf16 v[100:103], v[178:181], v[206:209], v[100:103]
	v_mfma_f32_16x16x32_bf16 v[96:99], v[186:189], v[206:209], v[96:99]
	v_mfma_f32_16x16x32_bf16 v[84:87], v[178:181], v[214:217], v[84:87]
	v_mfma_f32_16x16x32_bf16 v[80:83], v[186:189], v[214:217], v[80:83]
	v_mfma_f32_16x16x32_bf16 v[68:71], v[178:181], v[222:225], v[68:71]
	v_mfma_f32_16x16x32_bf16 v[64:67], v[186:189], v[222:225], v[64:67]
	s_setprio 0
	s_barrier
	s_add_i32 s40, s66, s3
	v_lshl_add_u64 v[156:157], v[156:157], 0, s[12:13]
	s_mov_b32 m0, s40
	ds_read_b128 v[190:193], v155 offset:49152
	ds_read_b128 v[198:201], v155 offset:50176
	ds_read_b128 v[202:205], v155 offset:51200
	ds_read_b128 v[206:209], v155 offset:52224
	ds_read_b128 v[210:213], v155 offset:53248
	ds_read_b128 v[214:217], v155 offset:54272
	ds_read_b128 v[218:221], v155 offset:55296
	ds_read_b128 v[222:225], v155 offset:56320
	global_load_lds_dwordx4 v[156:157], off
	s_add_i32 m0, s40, 0x2000
	s_add_u32 s8, s8, 0x40080
	v_lshl_add_u64 v[156:157], v[226:227], 0, s[12:13]
	s_addc_u32 s9, s9, 0
	s_add_i32 s40, s67, s3
	global_load_lds_dwordx4 v[156:157], off
	v_lshl_add_u64 v[156:157], s[8:9], 0, v[130:131]
	s_mov_b32 m0, s40
	s_nop 0
	global_load_lds_dwordx4 v[156:157], off
	v_lshl_add_u64 v[156:157], s[8:9], 0, v[134:135]
	s_add_i32 m0, s40, 0x2000
	s_nop 0
	global_load_lds_dwordx4 v[156:157], off
	v_lshl_add_u64 v[156:157], v[228:229], 0, s[12:13]
	s_mov_b32 m0, s19
	s_nop 0
	global_load_lds_dwordx4 v[156:157], off
	v_lshl_add_u64 v[156:157], v[230:231], 0, s[12:13]
	s_mov_b32 m0, s33
	s_nop 0
	global_load_lds_dwordx4 v[156:157], off
	s_waitcnt vmcnt(8)
	s_waitcnt lgkmcnt(0)
	s_barrier
	s_setprio 1
	s_waitcnt lgkmcnt(0)
	v_mfma_f32_16x16x32_bf16 v[60:63], v[144:147], v[190:193], v[60:63]
	v_mfma_f32_16x16x32_bf16 v[56:59], v[166:169], v[190:193], v[56:59]
	v_mfma_f32_16x16x32_bf16 v[44:47], v[144:147], v[202:205], v[44:47]
	v_mfma_f32_16x16x32_bf16 v[40:43], v[166:169], v[202:205], v[40:43]
	v_mfma_f32_16x16x32_bf16 v[28:31], v[144:147], v[210:213], v[28:31]
	v_mfma_f32_16x16x32_bf16 v[24:27], v[166:169], v[210:213], v[24:27]
	v_mfma_f32_16x16x32_bf16 v[12:15], v[144:147], v[218:221], v[12:15]
	v_mfma_f32_16x16x32_bf16 v[8:11], v[166:169], v[218:221], v[8:11]
	v_mfma_f32_16x16x32_bf16 v[60:63], v[162:165], v[198:201], v[60:63]
	v_mfma_f32_16x16x32_bf16 v[56:59], v[170:173], v[198:201], v[56:59]
	v_mfma_f32_16x16x32_bf16 v[44:47], v[162:165], v[206:209], v[44:47]
	v_mfma_f32_16x16x32_bf16 v[40:43], v[170:173], v[206:209], v[40:43]
	v_mfma_f32_16x16x32_bf16 v[28:31], v[162:165], v[214:217], v[28:31]
	v_mfma_f32_16x16x32_bf16 v[24:27], v[170:173], v[214:217], v[24:27]
	v_mfma_f32_16x16x32_bf16 v[12:15], v[162:165], v[222:225], v[12:15]
	v_mfma_f32_16x16x32_bf16 v[8:11], v[170:173], v[222:225], v[8:11]
	v_mfma_f32_16x16x32_bf16 v[52:55], v[174:177], v[190:193], v[52:55]
	v_mfma_f32_16x16x32_bf16 v[48:51], v[182:185], v[190:193], v[48:51]
	v_mfma_f32_16x16x32_bf16 v[36:39], v[174:177], v[202:205], v[36:39]
	v_mfma_f32_16x16x32_bf16 v[32:35], v[182:185], v[202:205], v[32:35]
	v_mfma_f32_16x16x32_bf16 v[20:23], v[174:177], v[210:213], v[20:23]
	v_mfma_f32_16x16x32_bf16 v[16:19], v[182:185], v[210:213], v[16:19]
	v_mfma_f32_16x16x32_bf16 v[4:7], v[174:177], v[218:221], v[4:7]
	v_mfma_f32_16x16x32_bf16 v[0:3], v[182:185], v[218:221], v[0:3]
	v_mfma_f32_16x16x32_bf16 v[52:55], v[178:181], v[198:201], v[52:55]
	v_mfma_f32_16x16x32_bf16 v[48:51], v[186:189], v[198:201], v[48:51]
	v_mfma_f32_16x16x32_bf16 v[36:39], v[178:181], v[206:209], v[36:39]
	v_mfma_f32_16x16x32_bf16 v[32:35], v[186:189], v[206:209], v[32:35]
	v_mfma_f32_16x16x32_bf16 v[20:23], v[178:181], v[214:217], v[20:23]
	v_mfma_f32_16x16x32_bf16 v[16:19], v[186:189], v[214:217], v[16:19]
	v_mfma_f32_16x16x32_bf16 v[4:7], v[178:181], v[222:225], v[4:7]
	v_mfma_f32_16x16x32_bf16 v[0:3], v[186:189], v[222:225], v[0:3]
	s_setprio 0
	s_barrier
	s_add_i32 s65, s65, 2
	s_add_u32 s38, s38, 0x100
	s_addc_u32 s39, s39, 0
	s_add_u32 s61, s61, 0x100
	s_addc_u32 s64, s64, 0
	s_cmp_gt_u32 s65, 13
	s_cbranch_scc0 .LBB0_666
	s_and_b64 vcc, exec, s[14:15]
	s_cbranch_vccz .LBB0_669
	s_barrier

.LBB0_765:
	ds_read_b128 v[144:147], v154
	ds_read_b128 v[162:165], v154 offset:1024
	ds_read_b128 v[166:169], v154 offset:2048
	ds_read_b128 v[170:173], v154 offset:3072
	ds_read_b128 v[174:177], v155
	ds_read_b128 v[178:181], v155 offset:1024
	ds_read_b128 v[182:185], v155 offset:2048
	ds_read_b128 v[186:189], v155 offset:3072
	s_add_u32 s8, s30, 0xfffc0080
	s_addc_u32 s9, s31, -1
	s_cmp_eq_u32 s60, 12
	s_cselect_b32 s37, s15, s9
	s_cselect_b32 s36, s47, s8
	s_cselect_b32 s9, s13, s59
	s_cselect_b32 s8, s55, s58
	v_lshl_add_u64 v[148:149], s[30:31], 0, v[136:137]
	s_add_i32 m0, s4, 0xc000
	ds_read_b128 v[190:193], v156
	ds_read_b128 v[198:201], v156 offset:1024
	ds_read_b128 v[202:205], v156 offset:2048
	ds_read_b128 v[206:209], v156 offset:3072
	ds_read_b128 v[210:213], v156 offset:4096
	ds_read_b128 v[214:217], v156 offset:5120
	ds_read_b128 v[218:221], v156 offset:6144
	ds_read_b128 v[222:225], v156 offset:7168
	global_load_lds_dwordx4 v[148:149], off
	v_lshl_add_u64 v[148:149], s[30:31], 0, v[138:139]
	s_add_i32 m0, s4, 0xe000
	s_nop 0
	global_load_lds_dwordx4 v[148:149], off
	s_waitcnt vmcnt(8)
	s_waitcnt lgkmcnt(0)
	s_barrier
	s_setprio 1
	s_waitcnt lgkmcnt(0)
	v_mfma_f32_16x16x32_bf16 v[124:127], v[144:147], v[190:193], v[124:127]
	v_mfma_f32_16x16x32_bf16 v[120:123], v[166:169], v[190:193], v[120:123]
	v_mfma_f32_16x16x32_bf16 v[108:111], v[144:147], v[202:205], v[108:111]
	v_mfma_f32_16x16x32_bf16 v[104:107], v[166:169], v[202:205], v[104:107]
	v_mfma_f32_16x16x32_bf16 v[92:95], v[144:147], v[210:213], v[92:95]
	v_mfma_f32_16x16x32_bf16 v[88:91], v[166:169], v[210:213], v[88:91]
	v_mfma_f32_16x16x32_bf16 v[76:79], v[144:147], v[218:221], v[76:79]
	v_mfma_f32_16x16x32_bf16 v[72:75], v[166:169], v[218:221], v[72:75]
	v_mfma_f32_16x16x32_bf16 v[124:127], v[162:165], v[198:201], v[124:127]
	v_mfma_f32_16x16x32_bf16 v[120:123], v[170:173], v[198:201], v[120:123]
	v_mfma_f32_16x16x32_bf16 v[108:111], v[162:165], v[206:209], v[108:111]
	v_mfma_f32_16x16x32_bf16 v[104:107], v[170:173], v[206:209], v[104:107]
	v_mfma_f32_16x16x32_bf16 v[92:95], v[162:165], v[214:217], v[92:95]
	v_mfma_f32_16x16x32_bf16 v[88:91], v[170:173], v[214:217], v[88:91]
	v_mfma_f32_16x16x32_bf16 v[76:79], v[162:165], v[222:225], v[76:79]
	v_mfma_f32_16x16x32_bf16 v[72:75], v[170:173], v[222:225], v[72:75]
	v_mfma_f32_16x16x32_bf16 v[116:119], v[174:177], v[190:193], v[116:119]
	v_mfma_f32_16x16x32_bf16 v[112:115], v[182:185], v[190:193], v[112:115]
	v_mfma_f32_16x16x32_bf16 v[100:103], v[174:177], v[202:205], v[100:103]
	v_mfma_f32_16x16x32_bf16 v[96:99], v[182:185], v[202:205], v[96:99]
	v_mfma_f32_16x16x32_bf16 v[84:87], v[174:177], v[210:213], v[84:87]
	v_mfma_f32_16x16x32_bf16 v[80:83], v[182:185], v[210:213], v[80:83]
	v_mfma_f32_16x16x32_bf16 v[68:71], v[174:177], v[218:221], v[68:71]
	v_mfma_f32_16x16x32_bf16 v[64:67], v[182:185], v[218:221], v[64:67]
	v_mfma_f32_16x16x32_bf16 v[116:119], v[178:181], v[198:201], v[116:119]
	v_mfma_f32_16x16x32_bf16 v[112:115], v[186:189], v[198:201], v[112:115]
	v_mfma_f32_16x16x32_bf16 v[100:103], v[178:181], v[206:209], v[100:103]
	v_mfma_f32_16x16x32_bf16 v[96:99], v[186:189], v[206:209], v[96:99]
	v_mfma_f32_16x16x32_bf16 v[84:87], v[178:181], v[214:217], v[84:87]
	v_mfma_f32_16x16x32_bf16 v[80:83], v[186:189], v[214:217], v[80:83]
	v_mfma_f32_16x16x32_bf16 v[68:71], v[178:181], v[222:225], v[68:71]
	v_mfma_f32_16x16x32_bf16 v[64:67], v[186:189], v[222:225], v[64:67]
	s_setprio 0
	s_barrier
	s_add_i32 s61, s38, s3
	v_lshl_add_u64 v[148:149], s[8:9], 0, v[132:133]
	s_mov_b32 m0, s61
	ds_read_b128 v[190:193], v156 offset:16384
	ds_read_b128 v[198:201], v156 offset:17408
	ds_read_b128 v[202:205], v156 offset:18432
	ds_read_b128 v[206:209], v156 offset:19456
	ds_read_b128 v[210:213], v156 offset:20480
	ds_read_b128 v[214:217], v156 offset:21504
	ds_read_b128 v[218:221], v156 offset:22528
	ds_read_b128 v[222:225], v156 offset:23552
	global_load_lds_dwordx4 v[148:149], off
	s_add_i32 m0, s61, 0x2000
	s_add_u32 s64, s8, 0x40000
	v_lshl_add_u64 v[226:227], s[8:9], 0, v[128:129]
	s_addc_u32 s65, s9, 0
	s_add_i32 s61, s39, s3
	global_load_lds_dwordx4 v[226:227], off
	v_lshl_add_u64 v[228:229], s[64:65], 0, v[132:133]
	s_mov_b32 m0, s61
	v_lshl_add_u64 v[230:231], s[36:37], 0, v[130:131]
	global_load_lds_dwordx4 v[228:229], off
	v_lshl_add_u64 v[228:229], s[64:65], 0, v[128:129]
	s_add_i32 m0, s61, 0x2000
	s_nop 0
	global_load_lds_dwordx4 v[228:229], off
	v_lshl_add_u64 v[228:229], s[36:37], 0, v[134:135]
	s_mov_b32 m0, s4
	s_nop 0
	global_load_lds_dwordx4 v[228:229], off
	s_mov_b32 m0, s5
	s_nop 0
	global_load_lds_dwordx4 v[230:231], off
	s_waitcnt vmcnt(8)
	s_waitcnt lgkmcnt(0)
	s_barrier
	s_setprio 1
	s_waitcnt lgkmcnt(0)
	v_mfma_f32_16x16x32_bf16 v[60:63], v[144:147], v[190:193], v[60:63]
	v_mfma_f32_16x16x32_bf16 v[56:59], v[166:169], v[190:193], v[56:59]
	v_mfma_f32_16x16x32_bf16 v[44:47], v[144:147], v[202:205], v[44:47]
	v_mfma_f32_16x16x32_bf16 v[40:43], v[166:169], v[202:205], v[40:43]
	v_mfma_f32_16x16x32_bf16 v[28:31], v[144:147], v[210:213], v[28:31]
	v_mfma_f32_16x16x32_bf16 v[24:27], v[166:169], v[210:213], v[24:27]
	v_mfma_f32_16x16x32_bf16 v[12:15], v[144:147], v[218:221], v[12:15]
	v_mfma_f32_16x16x32_bf16 v[8:11], v[166:169], v[218:221], v[8:11]
	v_mfma_f32_16x16x32_bf16 v[60:63], v[162:165], v[198:201], v[60:63]
	v_mfma_f32_16x16x32_bf16 v[56:59], v[170:173], v[198:201], v[56:59]
	v_mfma_f32_16x16x32_bf16 v[44:47], v[162:165], v[206:209], v[44:47]
	v_mfma_f32_16x16x32_bf16 v[40:43], v[170:173], v[206:209], v[40:43]
	v_mfma_f32_16x16x32_bf16 v[28:31], v[162:165], v[214:217], v[28:31]
	v_mfma_f32_16x16x32_bf16 v[24:27], v[170:173], v[214:217], v[24:27]
	v_mfma_f32_16x16x32_bf16 v[12:15], v[162:165], v[222:225], v[12:15]
	v_mfma_f32_16x16x32_bf16 v[8:11], v[170:173], v[222:225], v[8:11]
	v_mfma_f32_16x16x32_bf16 v[52:55], v[174:177], v[190:193], v[52:55]
	v_mfma_f32_16x16x32_bf16 v[48:51], v[182:185], v[190:193], v[48:51]
	v_mfma_f32_16x16x32_bf16 v[36:39], v[174:177], v[202:205], v[36:39]
	v_mfma_f32_16x16x32_bf16 v[32:35], v[182:185], v[202:205], v[32:35]
	v_mfma_f32_16x16x32_bf16 v[20:23], v[174:177], v[210:213], v[20:23]
	v_mfma_f32_16x16x32_bf16 v[16:19], v[182:185], v[210:213], v[16:19]
	v_mfma_f32_16x16x32_bf16 v[4:7], v[174:177], v[218:221], v[4:7]
	v_mfma_f32_16x16x32_bf16 v[0:3], v[182:185], v[218:221], v[0:3]
	v_mfma_f32_16x16x32_bf16 v[52:55], v[178:181], v[198:201], v[52:55]
	v_mfma_f32_16x16x32_bf16 v[48:51], v[186:189], v[198:201], v[48:51]
	v_mfma_f32_16x16x32_bf16 v[36:39], v[178:181], v[206:209], v[36:39]
	v_mfma_f32_16x16x32_bf16 v[32:35], v[186:189], v[206:209], v[32:35]
	v_mfma_f32_16x16x32_bf16 v[20:23], v[178:181], v[214:217], v[20:23]
	v_mfma_f32_16x16x32_bf16 v[16:19], v[186:189], v[214:217], v[16:19]
	v_mfma_f32_16x16x32_bf16 v[4:7], v[178:181], v[222:225], v[4:7]
	v_mfma_f32_16x16x32_bf16 v[0:3], v[186:189], v[222:225], v[0:3]
	s_setprio 0
	s_barrier
	s_add_i32 s61, 0, 0x18000
	v_add_u32_e32 v157, s61, v151
	s_add_i32 s64, 0, 0x1c000
	ds_read_b128 v[144:147], v157
	ds_read_b128 v[162:165], v157 offset:1024
	ds_read_b128 v[166:169], v157 offset:2048
	ds_read_b128 v[170:173], v157 offset:3072
	v_add_u32_e32 v157, s64, v151
	ds_read_b128 v[174:177], v157
	ds_read_b128 v[178:181], v157 offset:1024
	ds_read_b128 v[182:185], v157 offset:2048
	ds_read_b128 v[186:189], v157 offset:3072
	s_add_u32 s36, s36, 0x40000
	s_addc_u32 s37, s37, 0
	s_mov_b32 m0, s16
	v_lshl_add_u64 v[232:233], s[36:37], 0, v[134:135]
	ds_read_b128 v[190:193], v156 offset:32768
	ds_read_b128 v[198:201], v156 offset:33792
	ds_read_b128 v[202:205], v156 offset:34816
	ds_read_b128 v[206:209], v156 offset:35840
	ds_read_b128 v[210:213], v156 offset:36864
	ds_read_b128 v[214:217], v156 offset:37888
	ds_read_b128 v[218:221], v156 offset:38912
	ds_read_b128 v[222:225], v156 offset:39936
	global_load_lds_dwordx4 v[232:233], off
	v_lshl_add_u64 v[232:233], s[36:37], 0, v[130:131]
	s_mov_b32 m0, s17
	s_nop 0
	global_load_lds_dwordx4 v[232:233], off
	s_waitcnt vmcnt(8)
	s_waitcnt lgkmcnt(0)
	s_barrier
	s_setprio 1
	s_waitcnt lgkmcnt(0)
	v_mfma_f32_16x16x32_bf16 v[124:127], v[144:147], v[190:193], v[124:127]
	v_mfma_f32_16x16x32_bf16 v[120:123], v[166:169], v[190:193], v[120:123]
	v_mfma_f32_16x16x32_bf16 v[108:111], v[144:147], v[202:205], v[108:111]
	v_mfma_f32_16x16x32_bf16 v[104:107], v[166:169], v[202:205], v[104:107]
	v_mfma_f32_16x16x32_bf16 v[92:95], v[144:147], v[210:213], v[92:95]
	v_mfma_f32_16x16x32_bf16 v[88:91], v[166:169], v[210:213], v[88:91]
	v_mfma_f32_16x16x32_bf16 v[76:79], v[144:147], v[218:221], v[76:79]
	v_mfma_f32_16x16x32_bf16 v[72:75], v[166:169], v[218:221], v[72:75]
	v_mfma_f32_16x16x32_bf16 v[124:127], v[162:165], v[198:201], v[124:127]
	v_mfma_f32_16x16x32_bf16 v[120:123], v[170:173], v[198:201], v[120:123]
	v_mfma_f32_16x16x32_bf16 v[108:111], v[162:165], v[206:209], v[108:111]
	v_mfma_f32_16x16x32_bf16 v[104:107], v[170:173], v[206:209], v[104:107]
	v_mfma_f32_16x16x32_bf16 v[92:95], v[162:165], v[214:217], v[92:95]
	v_mfma_f32_16x16x32_bf16 v[88:91], v[170:173], v[214:217], v[88:91]
	v_mfma_f32_16x16x32_bf16 v[76:79], v[162:165], v[222:225], v[76:79]
	v_mfma_f32_16x16x32_bf16 v[72:75], v[170:173], v[222:225], v[72:75]
	v_mfma_f32_16x16x32_bf16 v[116:119], v[174:177], v[190:193], v[116:119]
	v_mfma_f32_16x16x32_bf16 v[112:115], v[182:185], v[190:193], v[112:115]
	v_mfma_f32_16x16x32_bf16 v[100:103], v[174:177], v[202:205], v[100:103]
	v_mfma_f32_16x16x32_bf16 v[96:99], v[182:185], v[202:205], v[96:99]
	v_mfma_f32_16x16x32_bf16 v[84:87], v[174:177], v[210:213], v[84:87]
	v_mfma_f32_16x16x32_bf16 v[80:83], v[182:185], v[210:213], v[80:83]
	v_mfma_f32_16x16x32_bf16 v[68:71], v[174:177], v[218:221], v[68:71]
	v_mfma_f32_16x16x32_bf16 v[64:67], v[182:185], v[218:221], v[64:67]
	v_mfma_f32_16x16x32_bf16 v[116:119], v[178:181], v[198:201], v[116:119]
	v_mfma_f32_16x16x32_bf16 v[112:115], v[186:189], v[198:201], v[112:115]
	v_mfma_f32_16x16x32_bf16 v[100:103], v[178:181], v[206:209], v[100:103]
	v_mfma_f32_16x16x32_bf16 v[96:99], v[186:189], v[206:209], v[96:99]
	v_mfma_f32_16x16x32_bf16 v[84:87], v[178:181], v[214:217], v[84:87]
	v_mfma_f32_16x16x32_bf16 v[80:83], v[186:189], v[214:217], v[80:83]
	v_mfma_f32_16x16x32_bf16 v[68:71], v[178:181], v[222:225], v[68:71]
	v_mfma_f32_16x16x32_bf16 v[64:67], v[186:189], v[222:225], v[64:67]
	s_setprio 0
	s_barrier
	s_add_i32 s36, s61, s3
	v_lshl_add_u64 v[148:149], v[148:149], 0, s[6:7]
	s_mov_b32 m0, s36
	ds_read_b128 v[190:193], v156 offset:49152
	ds_read_b128 v[198:201], v156 offset:50176
	ds_read_b128 v[202:205], v156 offset:51200
	ds_read_b128 v[206:209], v156 offset:52224
	ds_read_b128 v[210:213], v156 offset:53248
	ds_read_b128 v[214:217], v156 offset:54272
	ds_read_b128 v[218:221], v156 offset:55296
	ds_read_b128 v[222:225], v156 offset:56320
	global_load_lds_dwordx4 v[148:149], off
	s_add_i32 m0, s36, 0x2000
	s_add_u32 s8, s8, 0x40080
	v_lshl_add_u64 v[148:149], v[226:227], 0, s[6:7]
	s_addc_u32 s9, s9, 0
	s_add_i32 s36, s64, s3
	global_load_lds_dwordx4 v[148:149], off
	v_lshl_add_u64 v[148:149], s[8:9], 0, v[132:133]
	s_mov_b32 m0, s36
	s_nop 0
	global_load_lds_dwordx4 v[148:149], off
	v_lshl_add_u64 v[148:149], s[8:9], 0, v[128:129]
	s_add_i32 m0, s36, 0x2000
	s_nop 0
	global_load_lds_dwordx4 v[148:149], off
	v_lshl_add_u64 v[148:149], v[228:229], 0, s[6:7]
	s_mov_b32 m0, s29
	s_nop 0
	global_load_lds_dwordx4 v[148:149], off
	v_lshl_add_u64 v[148:149], v[230:231], 0, s[6:7]
	s_mov_b32 m0, s33
	s_nop 0
	global_load_lds_dwordx4 v[148:149], off
	s_waitcnt vmcnt(8)
	s_waitcnt lgkmcnt(0)
	s_barrier
	s_setprio 1
	s_waitcnt lgkmcnt(0)
	v_mfma_f32_16x16x32_bf16 v[60:63], v[144:147], v[190:193], v[60:63]
	v_mfma_f32_16x16x32_bf16 v[56:59], v[166:169], v[190:193], v[56:59]
	v_mfma_f32_16x16x32_bf16 v[44:47], v[144:147], v[202:205], v[44:47]
	v_mfma_f32_16x16x32_bf16 v[40:43], v[166:169], v[202:205], v[40:43]
	v_mfma_f32_16x16x32_bf16 v[28:31], v[144:147], v[210:213], v[28:31]
	v_mfma_f32_16x16x32_bf16 v[24:27], v[166:169], v[210:213], v[24:27]
	v_mfma_f32_16x16x32_bf16 v[12:15], v[144:147], v[218:221], v[12:15]
	v_mfma_f32_16x16x32_bf16 v[8:11], v[166:169], v[218:221], v[8:11]
	v_mfma_f32_16x16x32_bf16 v[60:63], v[162:165], v[198:201], v[60:63]
	v_mfma_f32_16x16x32_bf16 v[56:59], v[170:173], v[198:201], v[56:59]
	v_mfma_f32_16x16x32_bf16 v[44:47], v[162:165], v[206:209], v[44:47]
	v_mfma_f32_16x16x32_bf16 v[40:43], v[170:173], v[206:209], v[40:43]
	v_mfma_f32_16x16x32_bf16 v[28:31], v[162:165], v[214:217], v[28:31]
	v_mfma_f32_16x16x32_bf16 v[24:27], v[170:173], v[214:217], v[24:27]
	v_mfma_f32_16x16x32_bf16 v[12:15], v[162:165], v[222:225], v[12:15]
	v_mfma_f32_16x16x32_bf16 v[8:11], v[170:173], v[222:225], v[8:11]
	v_mfma_f32_16x16x32_bf16 v[52:55], v[174:177], v[190:193], v[52:55]
	v_mfma_f32_16x16x32_bf16 v[48:51], v[182:185], v[190:193], v[48:51]
	v_mfma_f32_16x16x32_bf16 v[36:39], v[174:177], v[202:205], v[36:39]
	v_mfma_f32_16x16x32_bf16 v[32:35], v[182:185], v[202:205], v[32:35]
	v_mfma_f32_16x16x32_bf16 v[20:23], v[174:177], v[210:213], v[20:23]
	v_mfma_f32_16x16x32_bf16 v[16:19], v[182:185], v[210:213], v[16:19]
	v_mfma_f32_16x16x32_bf16 v[4:7], v[174:177], v[218:221], v[4:7]
	v_mfma_f32_16x16x32_bf16 v[0:3], v[182:185], v[218:221], v[0:3]
	v_mfma_f32_16x16x32_bf16 v[52:55], v[178:181], v[198:201], v[52:55]
	v_mfma_f32_16x16x32_bf16 v[48:51], v[186:189], v[198:201], v[48:51]
	v_mfma_f32_16x16x32_bf16 v[36:39], v[178:181], v[206:209], v[36:39]
	v_mfma_f32_16x16x32_bf16 v[32:35], v[186:189], v[206:209], v[32:35]
	v_mfma_f32_16x16x32_bf16 v[20:23], v[178:181], v[214:217], v[20:23]
	v_mfma_f32_16x16x32_bf16 v[16:19], v[186:189], v[214:217], v[16:19]
	v_mfma_f32_16x16x32_bf16 v[4:7], v[178:181], v[222:225], v[4:7]
	v_mfma_f32_16x16x32_bf16 v[0:3], v[186:189], v[222:225], v[0:3]
	s_setprio 0
	s_barrier
	s_add_i32 s60, s60, 2
	s_add_u32 s30, s30, 0x100
	s_addc_u32 s31, s31, 0
	s_add_u32 s58, s58, 0x100
	s_addc_u32 s59, s59, 0
	s_cmp_gt_u32 s60, 13
	s_cbranch_scc0 .LBB0_765
	s_and_b64 vcc, exec, s[10:11]
	s_cbranch_vccz .LBB0_768
	s_barrier

.LBB0_841:
	ds_read_b128 v[144:147], v153
	ds_read_b128 v[162:165], v153 offset:1024
	ds_read_b128 v[166:169], v153 offset:2048
	ds_read_b128 v[170:173], v153 offset:3072
	ds_read_b128 v[174:177], v154
	ds_read_b128 v[178:181], v154 offset:1024
	ds_read_b128 v[182:185], v154 offset:2048
	ds_read_b128 v[186:189], v154 offset:3072
	s_add_u32 s8, s36, 0xfff00080
	s_addc_u32 s9, s37, -1
	s_cmp_eq_u32 s65, 60
	s_cselect_b32 s39, s25, s9
	s_cselect_b32 s38, s31, s8
	s_cselect_b32 s9, s21, s64
	s_cselect_b32 s8, s60, s61
	v_lshl_add_u64 v[156:157], s[36:37], 0, v[136:137]
	s_add_i32 m0, s4, 0xc000
	ds_read_b128 v[190:193], v155
	ds_read_b128 v[198:201], v155 offset:1024
	ds_read_b128 v[202:205], v155 offset:2048
	ds_read_b128 v[206:209], v155 offset:3072
	ds_read_b128 v[210:213], v155 offset:4096
	ds_read_b128 v[214:217], v155 offset:5120
	ds_read_b128 v[218:221], v155 offset:6144
	ds_read_b128 v[222:225], v155 offset:7168
	global_load_lds_dwordx4 v[156:157], off
	v_lshl_add_u64 v[156:157], s[36:37], 0, v[138:139]
	s_add_i32 m0, s4, 0xe000
	s_nop 0
	global_load_lds_dwordx4 v[156:157], off
	s_waitcnt vmcnt(8)
	s_waitcnt lgkmcnt(0)
	s_barrier
	s_setprio 1
	s_waitcnt lgkmcnt(0)
	v_mfma_f32_16x16x32_bf16 v[124:127], v[144:147], v[190:193], v[124:127]
	v_mfma_f32_16x16x32_bf16 v[120:123], v[166:169], v[190:193], v[120:123]
	v_mfma_f32_16x16x32_bf16 v[108:111], v[144:147], v[202:205], v[108:111]
	v_mfma_f32_16x16x32_bf16 v[104:107], v[166:169], v[202:205], v[104:107]
	v_mfma_f32_16x16x32_bf16 v[92:95], v[144:147], v[210:213], v[92:95]
	v_mfma_f32_16x16x32_bf16 v[88:91], v[166:169], v[210:213], v[88:91]
	v_mfma_f32_16x16x32_bf16 v[76:79], v[144:147], v[218:221], v[76:79]
	v_mfma_f32_16x16x32_bf16 v[72:75], v[166:169], v[218:221], v[72:75]
	v_mfma_f32_16x16x32_bf16 v[124:127], v[162:165], v[198:201], v[124:127]
	v_mfma_f32_16x16x32_bf16 v[120:123], v[170:173], v[198:201], v[120:123]
	v_mfma_f32_16x16x32_bf16 v[108:111], v[162:165], v[206:209], v[108:111]
	v_mfma_f32_16x16x32_bf16 v[104:107], v[170:173], v[206:209], v[104:107]
	v_mfma_f32_16x16x32_bf16 v[92:95], v[162:165], v[214:217], v[92:95]
	v_mfma_f32_16x16x32_bf16 v[88:91], v[170:173], v[214:217], v[88:91]
	v_mfma_f32_16x16x32_bf16 v[76:79], v[162:165], v[222:225], v[76:79]
	v_mfma_f32_16x16x32_bf16 v[72:75], v[170:173], v[222:225], v[72:75]
	v_mfma_f32_16x16x32_bf16 v[116:119], v[174:177], v[190:193], v[116:119]
	v_mfma_f32_16x16x32_bf16 v[112:115], v[182:185], v[190:193], v[112:115]
	v_mfma_f32_16x16x32_bf16 v[100:103], v[174:177], v[202:205], v[100:103]
	v_mfma_f32_16x16x32_bf16 v[96:99], v[182:185], v[202:205], v[96:99]
	v_mfma_f32_16x16x32_bf16 v[84:87], v[174:177], v[210:213], v[84:87]
	v_mfma_f32_16x16x32_bf16 v[80:83], v[182:185], v[210:213], v[80:83]
	v_mfma_f32_16x16x32_bf16 v[68:71], v[174:177], v[218:221], v[68:71]
	v_mfma_f32_16x16x32_bf16 v[64:67], v[182:185], v[218:221], v[64:67]
	v_mfma_f32_16x16x32_bf16 v[116:119], v[178:181], v[198:201], v[116:119]
	v_mfma_f32_16x16x32_bf16 v[112:115], v[186:189], v[198:201], v[112:115]
	v_mfma_f32_16x16x32_bf16 v[100:103], v[178:181], v[206:209], v[100:103]
	v_mfma_f32_16x16x32_bf16 v[96:99], v[186:189], v[206:209], v[96:99]
	v_mfma_f32_16x16x32_bf16 v[84:87], v[178:181], v[214:217], v[84:87]
	v_mfma_f32_16x16x32_bf16 v[80:83], v[186:189], v[214:217], v[80:83]
	v_mfma_f32_16x16x32_bf16 v[68:71], v[178:181], v[222:225], v[68:71]
	v_mfma_f32_16x16x32_bf16 v[64:67], v[186:189], v[222:225], v[64:67]
	s_setprio 0
	s_barrier
	s_add_i32 s66, s55, s3
	v_lshl_add_u64 v[156:157], s[8:9], 0, v[130:131]
	s_mov_b32 m0, s66
	ds_read_b128 v[190:193], v155 offset:16384
	ds_read_b128 v[198:201], v155 offset:17408
	ds_read_b128 v[202:205], v155 offset:18432
	ds_read_b128 v[206:209], v155 offset:19456
	ds_read_b128 v[210:213], v155 offset:20480
	ds_read_b128 v[214:217], v155 offset:21504
	ds_read_b128 v[218:221], v155 offset:22528
	ds_read_b128 v[222:225], v155 offset:23552
	global_load_lds_dwordx4 v[156:157], off
	s_add_i32 m0, s66, 0x2000
	s_add_u32 s66, s8, 0x100000
	v_lshl_add_u64 v[226:227], s[8:9], 0, v[134:135]
	s_addc_u32 s67, s9, 0
	s_add_i32 s73, s58, s3
	global_load_lds_dwordx4 v[226:227], off
	v_lshl_add_u64 v[228:229], s[66:67], 0, v[130:131]
	s_mov_b32 m0, s73
	v_lshl_add_u64 v[230:231], s[38:39], 0, v[132:133]
	global_load_lds_dwordx4 v[228:229], off
	v_lshl_add_u64 v[228:229], s[66:67], 0, v[134:135]
	s_add_i32 m0, s73, 0x2000
	s_nop 0
	global_load_lds_dwordx4 v[228:229], off
	v_lshl_add_u64 v[228:229], s[38:39], 0, v[128:129]
	s_mov_b32 m0, s4
	s_nop 0
	global_load_lds_dwordx4 v[228:229], off
	s_mov_b32 m0, s5
	s_nop 0
	global_load_lds_dwordx4 v[230:231], off
	s_waitcnt vmcnt(8)
	s_waitcnt lgkmcnt(0)
	s_barrier
	s_setprio 1
	s_waitcnt lgkmcnt(0)
	v_mfma_f32_16x16x32_bf16 v[60:63], v[144:147], v[190:193], v[60:63]
	v_mfma_f32_16x16x32_bf16 v[56:59], v[166:169], v[190:193], v[56:59]
	v_mfma_f32_16x16x32_bf16 v[44:47], v[144:147], v[202:205], v[44:47]
	v_mfma_f32_16x16x32_bf16 v[40:43], v[166:169], v[202:205], v[40:43]
	v_mfma_f32_16x16x32_bf16 v[28:31], v[144:147], v[210:213], v[28:31]
	v_mfma_f32_16x16x32_bf16 v[24:27], v[166:169], v[210:213], v[24:27]
	v_mfma_f32_16x16x32_bf16 v[12:15], v[144:147], v[218:221], v[12:15]
	v_mfma_f32_16x16x32_bf16 v[8:11], v[166:169], v[218:221], v[8:11]
	v_mfma_f32_16x16x32_bf16 v[60:63], v[162:165], v[198:201], v[60:63]
	v_mfma_f32_16x16x32_bf16 v[56:59], v[170:173], v[198:201], v[56:59]
	v_mfma_f32_16x16x32_bf16 v[44:47], v[162:165], v[206:209], v[44:47]
	v_mfma_f32_16x16x32_bf16 v[40:43], v[170:173], v[206:209], v[40:43]
	v_mfma_f32_16x16x32_bf16 v[28:31], v[162:165], v[214:217], v[28:31]
	v_mfma_f32_16x16x32_bf16 v[24:27], v[170:173], v[214:217], v[24:27]
	v_mfma_f32_16x16x32_bf16 v[12:15], v[162:165], v[222:225], v[12:15]
	v_mfma_f32_16x16x32_bf16 v[8:11], v[170:173], v[222:225], v[8:11]
	v_mfma_f32_16x16x32_bf16 v[52:55], v[174:177], v[190:193], v[52:55]
	v_mfma_f32_16x16x32_bf16 v[48:51], v[182:185], v[190:193], v[48:51]
	v_mfma_f32_16x16x32_bf16 v[36:39], v[174:177], v[202:205], v[36:39]
	v_mfma_f32_16x16x32_bf16 v[32:35], v[182:185], v[202:205], v[32:35]
	v_mfma_f32_16x16x32_bf16 v[20:23], v[174:177], v[210:213], v[20:23]
	v_mfma_f32_16x16x32_bf16 v[16:19], v[182:185], v[210:213], v[16:19]
	v_mfma_f32_16x16x32_bf16 v[4:7], v[174:177], v[218:221], v[4:7]
	v_mfma_f32_16x16x32_bf16 v[0:3], v[182:185], v[218:221], v[0:3]
	v_mfma_f32_16x16x32_bf16 v[52:55], v[178:181], v[198:201], v[52:55]
	v_mfma_f32_16x16x32_bf16 v[48:51], v[186:189], v[198:201], v[48:51]
	v_mfma_f32_16x16x32_bf16 v[36:39], v[178:181], v[206:209], v[36:39]
	v_mfma_f32_16x16x32_bf16 v[32:35], v[186:189], v[206:209], v[32:35]
	v_mfma_f32_16x16x32_bf16 v[20:23], v[178:181], v[214:217], v[20:23]
	v_mfma_f32_16x16x32_bf16 v[16:19], v[186:189], v[214:217], v[16:19]
	v_mfma_f32_16x16x32_bf16 v[4:7], v[178:181], v[222:225], v[4:7]
	v_mfma_f32_16x16x32_bf16 v[0:3], v[186:189], v[222:225], v[0:3]
	s_setprio 0
	s_barrier
	s_add_i32 s66, 0, 0x18000
	v_add_u32_e32 v158, s66, v149
	s_add_i32 s67, 0, 0x1c000
	ds_read_b128 v[144:147], v158
	ds_read_b128 v[162:165], v158 offset:1024
	ds_read_b128 v[166:169], v158 offset:2048
	ds_read_b128 v[170:173], v158 offset:3072
	v_add_u32_e32 v158, s67, v149
	ds_read_b128 v[174:177], v158
	ds_read_b128 v[178:181], v158 offset:1024
	ds_read_b128 v[182:185], v158 offset:2048
	ds_read_b128 v[186:189], v158 offset:3072
	s_add_u32 s38, s38, 0x100000
	s_addc_u32 s39, s39, 0
	s_mov_b32 m0, s16
	v_lshl_add_u64 v[232:233], s[38:39], 0, v[128:129]
	ds_read_b128 v[190:193], v155 offset:32768
	ds_read_b128 v[198:201], v155 offset:33792
	ds_read_b128 v[202:205], v155 offset:34816
	ds_read_b128 v[206:209], v155 offset:35840
	ds_read_b128 v[210:213], v155 offset:36864
	ds_read_b128 v[214:217], v155 offset:37888
	ds_read_b128 v[218:221], v155 offset:38912
	ds_read_b128 v[222:225], v155 offset:39936
	global_load_lds_dwordx4 v[232:233], off
	v_lshl_add_u64 v[232:233], s[38:39], 0, v[132:133]
	s_mov_b32 m0, s17
	s_nop 0
	global_load_lds_dwordx4 v[232:233], off
	s_waitcnt vmcnt(8)
	s_waitcnt lgkmcnt(0)
	s_barrier
	s_setprio 1
	s_waitcnt lgkmcnt(0)
	v_mfma_f32_16x16x32_bf16 v[124:127], v[144:147], v[190:193], v[124:127]
	v_mfma_f32_16x16x32_bf16 v[120:123], v[166:169], v[190:193], v[120:123]
	v_mfma_f32_16x16x32_bf16 v[108:111], v[144:147], v[202:205], v[108:111]
	v_mfma_f32_16x16x32_bf16 v[104:107], v[166:169], v[202:205], v[104:107]
	v_mfma_f32_16x16x32_bf16 v[92:95], v[144:147], v[210:213], v[92:95]
	v_mfma_f32_16x16x32_bf16 v[88:91], v[166:169], v[210:213], v[88:91]
	v_mfma_f32_16x16x32_bf16 v[76:79], v[144:147], v[218:221], v[76:79]
	v_mfma_f32_16x16x32_bf16 v[72:75], v[166:169], v[218:221], v[72:75]
	v_mfma_f32_16x16x32_bf16 v[124:127], v[162:165], v[198:201], v[124:127]
	v_mfma_f32_16x16x32_bf16 v[120:123], v[170:173], v[198:201], v[120:123]
	v_mfma_f32_16x16x32_bf16 v[108:111], v[162:165], v[206:209], v[108:111]
	v_mfma_f32_16x16x32_bf16 v[104:107], v[170:173], v[206:209], v[104:107]
	v_mfma_f32_16x16x32_bf16 v[92:95], v[162:165], v[214:217], v[92:95]
	v_mfma_f32_16x16x32_bf16 v[88:91], v[170:173], v[214:217], v[88:91]
	v_mfma_f32_16x16x32_bf16 v[76:79], v[162:165], v[222:225], v[76:79]
	v_mfma_f32_16x16x32_bf16 v[72:75], v[170:173], v[222:225], v[72:75]
	v_mfma_f32_16x16x32_bf16 v[116:119], v[174:177], v[190:193], v[116:119]
	v_mfma_f32_16x16x32_bf16 v[112:115], v[182:185], v[190:193], v[112:115]
	v_mfma_f32_16x16x32_bf16 v[100:103], v[174:177], v[202:205], v[100:103]
	v_mfma_f32_16x16x32_bf16 v[96:99], v[182:185], v[202:205], v[96:99]
	v_mfma_f32_16x16x32_bf16 v[84:87], v[174:177], v[210:213], v[84:87]
	v_mfma_f32_16x16x32_bf16 v[80:83], v[182:185], v[210:213], v[80:83]
	v_mfma_f32_16x16x32_bf16 v[68:71], v[174:177], v[218:221], v[68:71]
	v_mfma_f32_16x16x32_bf16 v[64:67], v[182:185], v[218:221], v[64:67]
	v_mfma_f32_16x16x32_bf16 v[116:119], v[178:181], v[198:201], v[116:119]
	v_mfma_f32_16x16x32_bf16 v[112:115], v[186:189], v[198:201], v[112:115]
	v_mfma_f32_16x16x32_bf16 v[100:103], v[178:181], v[206:209], v[100:103]
	v_mfma_f32_16x16x32_bf16 v[96:99], v[186:189], v[206:209], v[96:99]
	v_mfma_f32_16x16x32_bf16 v[84:87], v[178:181], v[214:217], v[84:87]
	v_mfma_f32_16x16x32_bf16 v[80:83], v[186:189], v[214:217], v[80:83]
	v_mfma_f32_16x16x32_bf16 v[68:71], v[178:181], v[222:225], v[68:71]
	v_mfma_f32_16x16x32_bf16 v[64:67], v[186:189], v[222:225], v[64:67]
	s_setprio 0
	s_barrier
	s_add_i32 s38, s66, s3
	v_lshl_add_u64 v[156:157], v[156:157], 0, s[12:13]
	s_mov_b32 m0, s38
	ds_read_b128 v[190:193], v155 offset:49152
	ds_read_b128 v[198:201], v155 offset:50176
	ds_read_b128 v[202:205], v155 offset:51200
	ds_read_b128 v[206:209], v155 offset:52224
	ds_read_b128 v[210:213], v155 offset:53248
	ds_read_b128 v[214:217], v155 offset:54272
	ds_read_b128 v[218:221], v155 offset:55296
	ds_read_b128 v[222:225], v155 offset:56320
	global_load_lds_dwordx4 v[156:157], off
	s_add_i32 m0, s38, 0x2000
	s_add_u32 s8, s8, 0x100080
	v_lshl_add_u64 v[156:157], v[226:227], 0, s[12:13]
	s_addc_u32 s9, s9, 0
	s_add_i32 s38, s67, s3
	global_load_lds_dwordx4 v[156:157], off
	v_lshl_add_u64 v[156:157], s[8:9], 0, v[130:131]
	s_mov_b32 m0, s38
	s_nop 0
	global_load_lds_dwordx4 v[156:157], off
	v_lshl_add_u64 v[156:157], s[8:9], 0, v[134:135]
	s_add_i32 m0, s38, 0x2000
	s_nop 0
	global_load_lds_dwordx4 v[156:157], off
	v_lshl_add_u64 v[156:157], v[228:229], 0, s[12:13]
	s_mov_b32 m0, s40
	s_nop 0
	global_load_lds_dwordx4 v[156:157], off
	v_lshl_add_u64 v[156:157], v[230:231], 0, s[12:13]
	s_mov_b32 m0, s41
	s_nop 0
	global_load_lds_dwordx4 v[156:157], off
	s_waitcnt vmcnt(8)
	s_waitcnt lgkmcnt(0)
	s_barrier
	s_setprio 1
	s_waitcnt lgkmcnt(0)
	v_mfma_f32_16x16x32_bf16 v[60:63], v[144:147], v[190:193], v[60:63]
	v_mfma_f32_16x16x32_bf16 v[56:59], v[166:169], v[190:193], v[56:59]
	v_mfma_f32_16x16x32_bf16 v[44:47], v[144:147], v[202:205], v[44:47]
	v_mfma_f32_16x16x32_bf16 v[40:43], v[166:169], v[202:205], v[40:43]
	v_mfma_f32_16x16x32_bf16 v[28:31], v[144:147], v[210:213], v[28:31]
	v_mfma_f32_16x16x32_bf16 v[24:27], v[166:169], v[210:213], v[24:27]
	v_mfma_f32_16x16x32_bf16 v[12:15], v[144:147], v[218:221], v[12:15]
	v_mfma_f32_16x16x32_bf16 v[8:11], v[166:169], v[218:221], v[8:11]
	v_mfma_f32_16x16x32_bf16 v[60:63], v[162:165], v[198:201], v[60:63]
	v_mfma_f32_16x16x32_bf16 v[56:59], v[170:173], v[198:201], v[56:59]
	v_mfma_f32_16x16x32_bf16 v[44:47], v[162:165], v[206:209], v[44:47]
	v_mfma_f32_16x16x32_bf16 v[40:43], v[170:173], v[206:209], v[40:43]
	v_mfma_f32_16x16x32_bf16 v[28:31], v[162:165], v[214:217], v[28:31]
	v_mfma_f32_16x16x32_bf16 v[24:27], v[170:173], v[214:217], v[24:27]
	v_mfma_f32_16x16x32_bf16 v[12:15], v[162:165], v[222:225], v[12:15]
	v_mfma_f32_16x16x32_bf16 v[8:11], v[170:173], v[222:225], v[8:11]
	v_mfma_f32_16x16x32_bf16 v[52:55], v[174:177], v[190:193], v[52:55]
	v_mfma_f32_16x16x32_bf16 v[48:51], v[182:185], v[190:193], v[48:51]
	v_mfma_f32_16x16x32_bf16 v[36:39], v[174:177], v[202:205], v[36:39]
	v_mfma_f32_16x16x32_bf16 v[32:35], v[182:185], v[202:205], v[32:35]
	v_mfma_f32_16x16x32_bf16 v[20:23], v[174:177], v[210:213], v[20:23]
	v_mfma_f32_16x16x32_bf16 v[16:19], v[182:185], v[210:213], v[16:19]
	v_mfma_f32_16x16x32_bf16 v[4:7], v[174:177], v[218:221], v[4:7]
	v_mfma_f32_16x16x32_bf16 v[0:3], v[182:185], v[218:221], v[0:3]
	v_mfma_f32_16x16x32_bf16 v[52:55], v[178:181], v[198:201], v[52:55]
	v_mfma_f32_16x16x32_bf16 v[48:51], v[186:189], v[198:201], v[48:51]
	v_mfma_f32_16x16x32_bf16 v[36:39], v[178:181], v[206:209], v[36:39]
	v_mfma_f32_16x16x32_bf16 v[32:35], v[186:189], v[206:209], v[32:35]
	v_mfma_f32_16x16x32_bf16 v[20:23], v[178:181], v[214:217], v[20:23]
	v_mfma_f32_16x16x32_bf16 v[16:19], v[186:189], v[214:217], v[16:19]
	v_mfma_f32_16x16x32_bf16 v[4:7], v[178:181], v[222:225], v[4:7]
	v_mfma_f32_16x16x32_bf16 v[0:3], v[186:189], v[222:225], v[0:3]
	s_setprio 0
	s_barrier
	s_add_i32 s65, s65, 2
	s_add_u32 s36, s36, 0x100
	s_addc_u32 s37, s37, 0
	s_add_u32 s61, s61, 0x100
	s_addc_u32 s64, s64, 0
	s_cmp_gt_u32 s65, 61
	s_cbranch_scc0 .LBB0_841
	s_and_b64 vcc, exec, s[14:15]
	s_cbranch_vccz .LBB0_844
	s_barrier

.LBB0_938:
	ds_read_b128 v[146:149], v169
	ds_read_b128 v[150:153], v169 offset:1024
	ds_read_b128 v[154:157], v169 offset:2048
	ds_read_b128 v[174:177], v169 offset:3072
	ds_read_b128 v[178:181], v170
	ds_read_b128 v[182:185], v170 offset:1024
	ds_read_b128 v[186:189], v170 offset:2048
	ds_read_b128 v[190:193], v170 offset:3072
	s_add_u32 s8, s26, 0xfffc0080
	s_addc_u32 s9, s27, -1
	s_cmp_eq_u32 s61, 12
	s_cselect_b32 s29, s15, s9
	s_cselect_b32 s28, s55, s8
	s_cselect_b32 s9, s13, s60
	s_cselect_b32 s8, s58, s59
	v_lshl_add_u64 v[230:231], s[26:27], 0, v[138:139]
	s_add_i32 m0, s5, 0xc000
	ds_read_b128 v[198:201], v171
	ds_read_b128 v[202:205], v171 offset:1024
	ds_read_b128 v[206:209], v171 offset:2048
	ds_read_b128 v[210:213], v171 offset:3072
	ds_read_b128 v[214:217], v171 offset:4096
	ds_read_b128 v[218:221], v171 offset:5120
	ds_read_b128 v[222:225], v171 offset:6144
	ds_read_b128 v[226:229], v171 offset:7168
	global_load_lds_dwordx4 v[230:231], off
	v_lshl_add_u64 v[230:231], s[26:27], 0, v[140:141]
	s_add_i32 m0, s5, 0xe000
	s_nop 0
	global_load_lds_dwordx4 v[230:231], off
	s_waitcnt vmcnt(8)
	s_waitcnt lgkmcnt(0)
	s_barrier
	s_setprio 1
	s_waitcnt lgkmcnt(0)
	v_mfma_f32_16x16x32_bf16 v[124:127], v[146:149], v[198:201], v[124:127]
	v_mfma_f32_16x16x32_bf16 v[120:123], v[154:157], v[198:201], v[120:123]
	v_mfma_f32_16x16x32_bf16 v[116:119], v[146:149], v[206:209], v[116:119]
	v_mfma_f32_16x16x32_bf16 v[108:111], v[154:157], v[206:209], v[108:111]
	v_mfma_f32_16x16x32_bf16 v[100:103], v[146:149], v[214:217], v[100:103]
	v_mfma_f32_16x16x32_bf16 v[92:95], v[154:157], v[214:217], v[92:95]
	v_mfma_f32_16x16x32_bf16 v[84:87], v[146:149], v[222:225], v[84:87]
	v_mfma_f32_16x16x32_bf16 v[76:79], v[154:157], v[222:225], v[76:79]
	v_mfma_f32_16x16x32_bf16 v[124:127], v[150:153], v[202:205], v[124:127]
	v_mfma_f32_16x16x32_bf16 v[120:123], v[174:177], v[202:205], v[120:123]
	v_mfma_f32_16x16x32_bf16 v[116:119], v[150:153], v[210:213], v[116:119]
	v_mfma_f32_16x16x32_bf16 v[108:111], v[174:177], v[210:213], v[108:111]
	v_mfma_f32_16x16x32_bf16 v[100:103], v[150:153], v[218:221], v[100:103]
	v_mfma_f32_16x16x32_bf16 v[92:95], v[174:177], v[218:221], v[92:95]
	v_mfma_f32_16x16x32_bf16 v[84:87], v[150:153], v[226:229], v[84:87]
	v_mfma_f32_16x16x32_bf16 v[76:79], v[174:177], v[226:229], v[76:79]
	v_mfma_f32_16x16x32_bf16 v[112:115], v[178:181], v[198:201], v[112:115]
	v_mfma_f32_16x16x32_bf16 v[104:107], v[186:189], v[198:201], v[104:107]
	v_mfma_f32_16x16x32_bf16 v[96:99], v[178:181], v[206:209], v[96:99]
	v_mfma_f32_16x16x32_bf16 v[88:91], v[186:189], v[206:209], v[88:91]
	v_mfma_f32_16x16x32_bf16 v[80:83], v[178:181], v[214:217], v[80:83]
	v_mfma_f32_16x16x32_bf16 v[72:75], v[186:189], v[214:217], v[72:75]
	v_mfma_f32_16x16x32_bf16 v[68:71], v[178:181], v[222:225], v[68:71]
	v_mfma_f32_16x16x32_bf16 v[64:67], v[186:189], v[222:225], v[64:67]
	v_mfma_f32_16x16x32_bf16 v[112:115], v[182:185], v[202:205], v[112:115]
	v_mfma_f32_16x16x32_bf16 v[104:107], v[190:193], v[202:205], v[104:107]
	v_mfma_f32_16x16x32_bf16 v[96:99], v[182:185], v[210:213], v[96:99]
	v_mfma_f32_16x16x32_bf16 v[88:91], v[190:193], v[210:213], v[88:91]
	v_mfma_f32_16x16x32_bf16 v[80:83], v[182:185], v[218:221], v[80:83]
	v_mfma_f32_16x16x32_bf16 v[72:75], v[190:193], v[218:221], v[72:75]
	v_mfma_f32_16x16x32_bf16 v[68:71], v[182:185], v[226:229], v[68:71]
	v_mfma_f32_16x16x32_bf16 v[64:67], v[190:193], v[226:229], v[64:67]
	s_setprio 0
	s_barrier
	s_add_i32 s62, s37, s3
	v_lshl_add_u64 v[230:231], s[8:9], 0, v[132:133]
	s_mov_b32 m0, s62
	ds_read_b128 v[198:201], v171 offset:16384
	ds_read_b128 v[202:205], v171 offset:17408
	ds_read_b128 v[206:209], v171 offset:18432
	ds_read_b128 v[210:213], v171 offset:19456
	ds_read_b128 v[214:217], v171 offset:20480
	ds_read_b128 v[218:221], v171 offset:21504
	ds_read_b128 v[222:225], v171 offset:22528
	ds_read_b128 v[226:229], v171 offset:23552
	global_load_lds_dwordx4 v[230:231], off
	s_add_i32 m0, s62, 0x2000
	s_add_u32 s62, s8, 0x40000
	v_lshl_add_u64 v[232:233], s[8:9], 0, v[128:129]
	s_addc_u32 s63, s9, 0
	s_add_i32 s64, s38, s3
	global_load_lds_dwordx4 v[232:233], off
	v_lshl_add_u64 v[234:235], s[62:63], 0, v[132:133]
	s_mov_b32 m0, s64
	v_lshl_add_u64 v[236:237], s[28:29], 0, v[130:131]
	global_load_lds_dwordx4 v[234:235], off
	v_lshl_add_u64 v[234:235], s[62:63], 0, v[128:129]
	s_add_i32 m0, s64, 0x2000
	s_nop 0
	global_load_lds_dwordx4 v[234:235], off
	v_lshl_add_u64 v[234:235], s[28:29], 0, v[134:135]
	s_mov_b32 m0, s5
	s_nop 0
	global_load_lds_dwordx4 v[234:235], off
	s_mov_b32 m0, s25
	s_nop 0
	global_load_lds_dwordx4 v[236:237], off
	s_waitcnt vmcnt(8)
	s_waitcnt lgkmcnt(0)
	s_barrier
	s_setprio 1
	s_waitcnt lgkmcnt(0)
	v_mfma_f32_16x16x32_bf16 v[60:63], v[146:149], v[198:201], v[60:63]
	v_mfma_f32_16x16x32_bf16 v[56:59], v[154:157], v[198:201], v[56:59]
	v_mfma_f32_16x16x32_bf16 v[52:55], v[146:149], v[206:209], v[52:55]
	v_mfma_f32_16x16x32_bf16 v[44:47], v[154:157], v[206:209], v[44:47]
	v_mfma_f32_16x16x32_bf16 v[32:35], v[146:149], v[214:217], v[32:35]
	v_mfma_f32_16x16x32_bf16 v[24:27], v[154:157], v[214:217], v[24:27]
	v_mfma_f32_16x16x32_bf16 v[20:23], v[146:149], v[222:225], v[20:23]
	v_mfma_f32_16x16x32_bf16 v[12:15], v[154:157], v[222:225], v[12:15]
	v_mfma_f32_16x16x32_bf16 v[60:63], v[150:153], v[202:205], v[60:63]
	v_mfma_f32_16x16x32_bf16 v[56:59], v[174:177], v[202:205], v[56:59]
	v_mfma_f32_16x16x32_bf16 v[52:55], v[150:153], v[210:213], v[52:55]
	v_mfma_f32_16x16x32_bf16 v[44:47], v[174:177], v[210:213], v[44:47]
	v_mfma_f32_16x16x32_bf16 v[32:35], v[150:153], v[218:221], v[32:35]
	v_mfma_f32_16x16x32_bf16 v[24:27], v[174:177], v[218:221], v[24:27]
	v_mfma_f32_16x16x32_bf16 v[20:23], v[150:153], v[226:229], v[20:23]
	v_mfma_f32_16x16x32_bf16 v[12:15], v[174:177], v[226:229], v[12:15]
	v_mfma_f32_16x16x32_bf16 v[48:51], v[178:181], v[198:201], v[48:51]
	v_mfma_f32_16x16x32_bf16 v[40:43], v[186:189], v[198:201], v[40:43]
	v_mfma_f32_16x16x32_bf16 v[36:39], v[178:181], v[206:209], v[36:39]
	v_mfma_f32_16x16x32_bf16 v[28:31], v[186:189], v[206:209], v[28:31]
	v_mfma_f32_16x16x32_bf16 v[16:19], v[178:181], v[214:217], v[16:19]
	v_mfma_f32_16x16x32_bf16 v[8:11], v[186:189], v[214:217], v[8:11]
	v_mfma_f32_16x16x32_bf16 v[4:7], v[178:181], v[222:225], v[4:7]
	v_mfma_f32_16x16x32_bf16 v[0:3], v[186:189], v[222:225], v[0:3]
	v_mfma_f32_16x16x32_bf16 v[48:51], v[182:185], v[202:205], v[48:51]
	v_mfma_f32_16x16x32_bf16 v[40:43], v[190:193], v[202:205], v[40:43]
	v_mfma_f32_16x16x32_bf16 v[36:39], v[182:185], v[210:213], v[36:39]
	v_mfma_f32_16x16x32_bf16 v[28:31], v[190:193], v[210:213], v[28:31]
	v_mfma_f32_16x16x32_bf16 v[16:19], v[182:185], v[218:221], v[16:19]
	v_mfma_f32_16x16x32_bf16 v[8:11], v[190:193], v[218:221], v[8:11]
	v_mfma_f32_16x16x32_bf16 v[4:7], v[182:185], v[226:229], v[4:7]
	v_mfma_f32_16x16x32_bf16 v[0:3], v[190:193], v[226:229], v[0:3]
	s_setprio 0
	s_barrier
	s_add_i32 s62, 0, 0x18000
	s_add_i32 s63, 0, 0x1c000
	v_add_u32_e32 v174, s62, v162
	v_add_u32_e32 v190, s63, v162
	ds_read_b128 v[146:149], v174
	ds_read_b128 v[150:153], v174 offset:1024
	ds_read_b128 v[154:157], v174 offset:2048
	ds_read_b128 v[174:177], v174 offset:3072
	ds_read_b128 v[178:181], v190
	ds_read_b128 v[182:185], v190 offset:1024
	ds_read_b128 v[186:189], v190 offset:2048
	ds_read_b128 v[190:193], v190 offset:3072
	s_add_u32 s28, s28, 0x40000
	s_addc_u32 s29, s29, 0
	s_mov_b32 m0, s30
	v_lshl_add_u64 v[238:239], s[28:29], 0, v[134:135]
	ds_read_b128 v[198:201], v171 offset:32768
	ds_read_b128 v[202:205], v171 offset:33792
	ds_read_b128 v[206:209], v171 offset:34816
	ds_read_b128 v[210:213], v171 offset:35840
	ds_read_b128 v[214:217], v171 offset:36864
	ds_read_b128 v[218:221], v171 offset:37888
	ds_read_b128 v[222:225], v171 offset:38912
	ds_read_b128 v[226:229], v171 offset:39936
	global_load_lds_dwordx4 v[238:239], off
	v_lshl_add_u64 v[238:239], s[28:29], 0, v[130:131]
	s_mov_b32 m0, s31
	s_nop 0
	global_load_lds_dwordx4 v[238:239], off
	s_waitcnt vmcnt(8)
	s_waitcnt lgkmcnt(0)
	s_barrier
	s_setprio 1
	s_waitcnt lgkmcnt(0)
	v_mfma_f32_16x16x32_bf16 v[124:127], v[146:149], v[198:201], v[124:127]
	v_mfma_f32_16x16x32_bf16 v[120:123], v[154:157], v[198:201], v[120:123]
	v_mfma_f32_16x16x32_bf16 v[116:119], v[146:149], v[206:209], v[116:119]
	v_mfma_f32_16x16x32_bf16 v[108:111], v[154:157], v[206:209], v[108:111]
	v_mfma_f32_16x16x32_bf16 v[100:103], v[146:149], v[214:217], v[100:103]
	v_mfma_f32_16x16x32_bf16 v[92:95], v[154:157], v[214:217], v[92:95]
	v_mfma_f32_16x16x32_bf16 v[84:87], v[146:149], v[222:225], v[84:87]
	v_mfma_f32_16x16x32_bf16 v[76:79], v[154:157], v[222:225], v[76:79]
	v_mfma_f32_16x16x32_bf16 v[124:127], v[150:153], v[202:205], v[124:127]
	v_mfma_f32_16x16x32_bf16 v[120:123], v[174:177], v[202:205], v[120:123]
	v_mfma_f32_16x16x32_bf16 v[116:119], v[150:153], v[210:213], v[116:119]
	v_mfma_f32_16x16x32_bf16 v[108:111], v[174:177], v[210:213], v[108:111]
	v_mfma_f32_16x16x32_bf16 v[100:103], v[150:153], v[218:221], v[100:103]
	v_mfma_f32_16x16x32_bf16 v[92:95], v[174:177], v[218:221], v[92:95]
	v_mfma_f32_16x16x32_bf16 v[84:87], v[150:153], v[226:229], v[84:87]
	v_mfma_f32_16x16x32_bf16 v[76:79], v[174:177], v[226:229], v[76:79]
	v_mfma_f32_16x16x32_bf16 v[112:115], v[178:181], v[198:201], v[112:115]
	v_mfma_f32_16x16x32_bf16 v[104:107], v[186:189], v[198:201], v[104:107]
	v_mfma_f32_16x16x32_bf16 v[96:99], v[178:181], v[206:209], v[96:99]
	v_mfma_f32_16x16x32_bf16 v[88:91], v[186:189], v[206:209], v[88:91]
	v_mfma_f32_16x16x32_bf16 v[80:83], v[178:181], v[214:217], v[80:83]
	v_mfma_f32_16x16x32_bf16 v[72:75], v[186:189], v[214:217], v[72:75]
	v_mfma_f32_16x16x32_bf16 v[68:71], v[178:181], v[222:225], v[68:71]
	v_mfma_f32_16x16x32_bf16 v[64:67], v[186:189], v[222:225], v[64:67]
	v_mfma_f32_16x16x32_bf16 v[112:115], v[182:185], v[202:205], v[112:115]
	v_mfma_f32_16x16x32_bf16 v[104:107], v[190:193], v[202:205], v[104:107]
	v_mfma_f32_16x16x32_bf16 v[96:99], v[182:185], v[210:213], v[96:99]
	v_mfma_f32_16x16x32_bf16 v[88:91], v[190:193], v[210:213], v[88:91]
	v_mfma_f32_16x16x32_bf16 v[80:83], v[182:185], v[218:221], v[80:83]
	v_mfma_f32_16x16x32_bf16 v[72:75], v[190:193], v[218:221], v[72:75]
	v_mfma_f32_16x16x32_bf16 v[68:71], v[182:185], v[226:229], v[68:71]
	v_mfma_f32_16x16x32_bf16 v[64:67], v[190:193], v[226:229], v[64:67]
	s_setprio 0
	s_barrier
	s_add_i32 s28, s62, s3
	v_lshl_add_u64 v[230:231], v[230:231], 0, s[6:7]
	s_mov_b32 m0, s28
	ds_read_b128 v[198:201], v171 offset:49152
	ds_read_b128 v[202:205], v171 offset:50176
	ds_read_b128 v[206:209], v171 offset:51200
	ds_read_b128 v[210:213], v171 offset:52224
	ds_read_b128 v[214:217], v171 offset:53248
	ds_read_b128 v[218:221], v171 offset:54272
	ds_read_b128 v[222:225], v171 offset:55296
	ds_read_b128 v[226:229], v171 offset:56320
	global_load_lds_dwordx4 v[230:231], off
	s_add_i32 m0, s28, 0x2000
	s_add_u32 s8, s8, 0x40080
	v_lshl_add_u64 v[230:231], v[232:233], 0, s[6:7]
	s_addc_u32 s9, s9, 0
	s_add_i32 s28, s63, s3
	global_load_lds_dwordx4 v[230:231], off
	v_lshl_add_u64 v[230:231], s[8:9], 0, v[132:133]
	s_mov_b32 m0, s28
	s_nop 0
	global_load_lds_dwordx4 v[230:231], off
	v_lshl_add_u64 v[230:231], s[8:9], 0, v[128:129]
	s_add_i32 m0, s28, 0x2000
	s_nop 0
	global_load_lds_dwordx4 v[230:231], off
	v_lshl_add_u64 v[230:231], v[234:235], 0, s[6:7]
	s_mov_b32 m0, s33
	s_nop 0
	global_load_lds_dwordx4 v[230:231], off
	v_lshl_add_u64 v[230:231], v[236:237], 0, s[6:7]
	s_mov_b32 m0, s36
	s_nop 0
	global_load_lds_dwordx4 v[230:231], off
	s_waitcnt vmcnt(8)
	s_waitcnt lgkmcnt(0)
	s_barrier
	s_setprio 1
	s_waitcnt lgkmcnt(0)
	v_mfma_f32_16x16x32_bf16 v[60:63], v[146:149], v[198:201], v[60:63]
	v_mfma_f32_16x16x32_bf16 v[56:59], v[154:157], v[198:201], v[56:59]
	v_mfma_f32_16x16x32_bf16 v[52:55], v[146:149], v[206:209], v[52:55]
	v_mfma_f32_16x16x32_bf16 v[44:47], v[154:157], v[206:209], v[44:47]
	v_mfma_f32_16x16x32_bf16 v[32:35], v[146:149], v[214:217], v[32:35]
	v_mfma_f32_16x16x32_bf16 v[24:27], v[154:157], v[214:217], v[24:27]
	v_mfma_f32_16x16x32_bf16 v[20:23], v[146:149], v[222:225], v[20:23]
	v_mfma_f32_16x16x32_bf16 v[12:15], v[154:157], v[222:225], v[12:15]
	v_mfma_f32_16x16x32_bf16 v[60:63], v[150:153], v[202:205], v[60:63]
	v_mfma_f32_16x16x32_bf16 v[56:59], v[174:177], v[202:205], v[56:59]
	v_mfma_f32_16x16x32_bf16 v[52:55], v[150:153], v[210:213], v[52:55]
	v_mfma_f32_16x16x32_bf16 v[44:47], v[174:177], v[210:213], v[44:47]
	v_mfma_f32_16x16x32_bf16 v[32:35], v[150:153], v[218:221], v[32:35]
	v_mfma_f32_16x16x32_bf16 v[24:27], v[174:177], v[218:221], v[24:27]
	v_mfma_f32_16x16x32_bf16 v[20:23], v[150:153], v[226:229], v[20:23]
	v_mfma_f32_16x16x32_bf16 v[12:15], v[174:177], v[226:229], v[12:15]
	v_mfma_f32_16x16x32_bf16 v[48:51], v[178:181], v[198:201], v[48:51]
	v_mfma_f32_16x16x32_bf16 v[40:43], v[186:189], v[198:201], v[40:43]
	v_mfma_f32_16x16x32_bf16 v[36:39], v[178:181], v[206:209], v[36:39]
	v_mfma_f32_16x16x32_bf16 v[28:31], v[186:189], v[206:209], v[28:31]
	v_mfma_f32_16x16x32_bf16 v[16:19], v[178:181], v[214:217], v[16:19]
	v_mfma_f32_16x16x32_bf16 v[8:11], v[186:189], v[214:217], v[8:11]
	v_mfma_f32_16x16x32_bf16 v[4:7], v[178:181], v[222:225], v[4:7]
	v_mfma_f32_16x16x32_bf16 v[0:3], v[186:189], v[222:225], v[0:3]
	v_mfma_f32_16x16x32_bf16 v[48:51], v[182:185], v[202:205], v[48:51]
	v_mfma_f32_16x16x32_bf16 v[40:43], v[190:193], v[202:205], v[40:43]
	v_mfma_f32_16x16x32_bf16 v[36:39], v[182:185], v[210:213], v[36:39]
	v_mfma_f32_16x16x32_bf16 v[28:31], v[190:193], v[210:213], v[28:31]
	v_mfma_f32_16x16x32_bf16 v[16:19], v[182:185], v[218:221], v[16:19]
	v_mfma_f32_16x16x32_bf16 v[8:11], v[190:193], v[218:221], v[8:11]
	v_mfma_f32_16x16x32_bf16 v[4:7], v[182:185], v[226:229], v[4:7]
	v_mfma_f32_16x16x32_bf16 v[0:3], v[190:193], v[226:229], v[0:3]
	s_setprio 0
	s_barrier
	s_add_i32 s61, s61, 2
	s_add_u32 s26, s26, 0x100
	s_addc_u32 s27, s27, 0
	s_add_u32 s59, s59, 0x100
	s_addc_u32 s60, s60, 0
	s_cmp_gt_u32 s61, 13
	s_cbranch_scc0 .LBB0_938
	s_and_b64 vcc, exec, s[10:11]
	s_cbranch_vccz .LBB0_941
	s_barrier

.LBB0_1226:
	ds_read_b128 v[144:147], v151
	ds_read_b128 v[154:157], v151 offset:1024
	ds_read_b128 v[158:161], v151 offset:2048
	ds_read_b128 v[162:165], v151 offset:3072
	ds_read_b128 v[166:169], v152
	ds_read_b128 v[170:173], v152 offset:1024
	ds_read_b128 v[174:177], v152 offset:2048
	ds_read_b128 v[178:181], v152 offset:3072
	s_add_u32 s8, s28, 0xfffc0080
	s_addc_u32 s9, s29, -1
	s_cmp_eq_u32 s58, 12
	s_cselect_b32 s31, s21, s9
	s_cselect_b32 s30, s27, s8
	s_cselect_b32 s9, s17, s57
	s_cselect_b32 s8, s53, s55
	v_lshl_add_u64 v[196:197], s[28:29], 0, v[136:137]
	s_add_i32 m0, s4, 0xc000
	ds_read_b128 v[182:185], v153
	ds_read_b128 v[186:189], v153 offset:1024
	ds_read_b128 v[190:193], v153 offset:2048
	ds_read_b128 v[200:203], v153 offset:3072
	ds_read_b128 v[204:207], v153 offset:4096
	ds_read_b128 v[208:211], v153 offset:5120
	ds_read_b128 v[212:215], v153 offset:6144
	ds_read_b128 v[216:219], v153 offset:7168
	global_load_lds_dwordx4 v[196:197], off
	v_lshl_add_u64 v[196:197], s[28:29], 0, v[138:139]
	s_add_i32 m0, s4, 0xe000
	s_nop 0
	global_load_lds_dwordx4 v[196:197], off
	s_waitcnt vmcnt(8)
	s_waitcnt lgkmcnt(0)
	s_barrier
	s_setprio 1
	s_waitcnt lgkmcnt(0)
	v_mfma_f32_16x16x32_bf16 v[124:127], v[144:147], v[182:185], v[124:127]
	v_mfma_f32_16x16x32_bf16 v[120:123], v[158:161], v[182:185], v[120:123]
	v_mfma_f32_16x16x32_bf16 v[108:111], v[144:147], v[190:193], v[108:111]
	v_mfma_f32_16x16x32_bf16 v[104:107], v[158:161], v[190:193], v[104:107]
	v_mfma_f32_16x16x32_bf16 v[92:95], v[144:147], v[204:207], v[92:95]
	v_mfma_f32_16x16x32_bf16 v[88:91], v[158:161], v[204:207], v[88:91]
	v_mfma_f32_16x16x32_bf16 v[76:79], v[144:147], v[212:215], v[76:79]
	v_mfma_f32_16x16x32_bf16 v[72:75], v[158:161], v[212:215], v[72:75]
	v_mfma_f32_16x16x32_bf16 v[124:127], v[154:157], v[186:189], v[124:127]
	v_mfma_f32_16x16x32_bf16 v[120:123], v[162:165], v[186:189], v[120:123]
	v_mfma_f32_16x16x32_bf16 v[108:111], v[154:157], v[200:203], v[108:111]
	v_mfma_f32_16x16x32_bf16 v[104:107], v[162:165], v[200:203], v[104:107]
	v_mfma_f32_16x16x32_bf16 v[92:95], v[154:157], v[208:211], v[92:95]
	v_mfma_f32_16x16x32_bf16 v[88:91], v[162:165], v[208:211], v[88:91]
	v_mfma_f32_16x16x32_bf16 v[76:79], v[154:157], v[216:219], v[76:79]
	v_mfma_f32_16x16x32_bf16 v[72:75], v[162:165], v[216:219], v[72:75]
	v_mfma_f32_16x16x32_bf16 v[116:119], v[166:169], v[182:185], v[116:119]
	v_mfma_f32_16x16x32_bf16 v[112:115], v[174:177], v[182:185], v[112:115]
	v_mfma_f32_16x16x32_bf16 v[100:103], v[166:169], v[190:193], v[100:103]
	v_mfma_f32_16x16x32_bf16 v[96:99], v[174:177], v[190:193], v[96:99]
	v_mfma_f32_16x16x32_bf16 v[84:87], v[166:169], v[204:207], v[84:87]
	v_mfma_f32_16x16x32_bf16 v[80:83], v[174:177], v[204:207], v[80:83]
	v_mfma_f32_16x16x32_bf16 v[68:71], v[166:169], v[212:215], v[68:71]
	v_mfma_f32_16x16x32_bf16 v[64:67], v[174:177], v[212:215], v[64:67]
	v_mfma_f32_16x16x32_bf16 v[116:119], v[170:173], v[186:189], v[116:119]
	v_mfma_f32_16x16x32_bf16 v[112:115], v[178:181], v[186:189], v[112:115]
	v_mfma_f32_16x16x32_bf16 v[100:103], v[170:173], v[200:203], v[100:103]
	v_mfma_f32_16x16x32_bf16 v[96:99], v[178:181], v[200:203], v[96:99]
	v_mfma_f32_16x16x32_bf16 v[84:87], v[170:173], v[208:211], v[84:87]
	v_mfma_f32_16x16x32_bf16 v[80:83], v[178:181], v[208:211], v[80:83]
	v_mfma_f32_16x16x32_bf16 v[68:71], v[170:173], v[216:219], v[68:71]
	v_mfma_f32_16x16x32_bf16 v[64:67], v[178:181], v[216:219], v[64:67]
	s_setprio 0
	s_barrier
	s_add_i32 s59, s40, s3
	v_lshl_add_u64 v[196:197], s[8:9], 0, v[130:131]
	s_mov_b32 m0, s59
	ds_read_b128 v[182:185], v153 offset:16384
	ds_read_b128 v[186:189], v153 offset:17408
	ds_read_b128 v[190:193], v153 offset:18432
	ds_read_b128 v[200:203], v153 offset:19456
	ds_read_b128 v[204:207], v153 offset:20480
	ds_read_b128 v[208:211], v153 offset:21504
	ds_read_b128 v[212:215], v153 offset:22528
	ds_read_b128 v[216:219], v153 offset:23552
	global_load_lds_dwordx4 v[196:197], off
	s_add_i32 m0, s59, 0x2000
	s_add_u32 s60, s8, 0x40000
	v_lshl_add_u64 v[220:221], s[8:9], 0, v[134:135]
	s_addc_u32 s61, s9, 0
	s_add_i32 s59, s41, s3
	global_load_lds_dwordx4 v[220:221], off
	v_lshl_add_u64 v[222:223], s[60:61], 0, v[130:131]
	s_mov_b32 m0, s59
	v_lshl_add_u64 v[224:225], s[30:31], 0, v[132:133]
	global_load_lds_dwordx4 v[222:223], off
	v_lshl_add_u64 v[222:223], s[60:61], 0, v[134:135]
	s_add_i32 m0, s59, 0x2000
	s_nop 0
	global_load_lds_dwordx4 v[222:223], off
	v_lshl_add_u64 v[222:223], s[30:31], 0, v[128:129]
	s_mov_b32 m0, s4
	s_nop 0
	global_load_lds_dwordx4 v[222:223], off
	s_mov_b32 m0, s5
	s_nop 0
	global_load_lds_dwordx4 v[224:225], off
	s_waitcnt vmcnt(8)
	s_waitcnt lgkmcnt(0)
	s_barrier
	s_setprio 1
	s_waitcnt lgkmcnt(0)
	v_mfma_f32_16x16x32_bf16 v[60:63], v[144:147], v[182:185], v[60:63]
	v_mfma_f32_16x16x32_bf16 v[56:59], v[158:161], v[182:185], v[56:59]
	v_mfma_f32_16x16x32_bf16 v[44:47], v[144:147], v[190:193], v[44:47]
	v_mfma_f32_16x16x32_bf16 v[40:43], v[158:161], v[190:193], v[40:43]
	v_mfma_f32_16x16x32_bf16 v[28:31], v[144:147], v[204:207], v[28:31]
	v_mfma_f32_16x16x32_bf16 v[24:27], v[158:161], v[204:207], v[24:27]
	v_mfma_f32_16x16x32_bf16 v[12:15], v[144:147], v[212:215], v[12:15]
	v_mfma_f32_16x16x32_bf16 v[8:11], v[158:161], v[212:215], v[8:11]
	v_mfma_f32_16x16x32_bf16 v[60:63], v[154:157], v[186:189], v[60:63]
	v_mfma_f32_16x16x32_bf16 v[56:59], v[162:165], v[186:189], v[56:59]
	v_mfma_f32_16x16x32_bf16 v[44:47], v[154:157], v[200:203], v[44:47]
	v_mfma_f32_16x16x32_bf16 v[40:43], v[162:165], v[200:203], v[40:43]
	v_mfma_f32_16x16x32_bf16 v[28:31], v[154:157], v[208:211], v[28:31]
	v_mfma_f32_16x16x32_bf16 v[24:27], v[162:165], v[208:211], v[24:27]
	v_mfma_f32_16x16x32_bf16 v[12:15], v[154:157], v[216:219], v[12:15]
	v_mfma_f32_16x16x32_bf16 v[8:11], v[162:165], v[216:219], v[8:11]
	v_mfma_f32_16x16x32_bf16 v[52:55], v[166:169], v[182:185], v[52:55]
	v_mfma_f32_16x16x32_bf16 v[48:51], v[174:177], v[182:185], v[48:51]
	v_mfma_f32_16x16x32_bf16 v[36:39], v[166:169], v[190:193], v[36:39]
	v_mfma_f32_16x16x32_bf16 v[32:35], v[174:177], v[190:193], v[32:35]
	v_mfma_f32_16x16x32_bf16 v[20:23], v[166:169], v[204:207], v[20:23]
	v_mfma_f32_16x16x32_bf16 v[16:19], v[174:177], v[204:207], v[16:19]
	v_mfma_f32_16x16x32_bf16 v[4:7], v[166:169], v[212:215], v[4:7]
	v_mfma_f32_16x16x32_bf16 v[0:3], v[174:177], v[212:215], v[0:3]
	v_mfma_f32_16x16x32_bf16 v[52:55], v[170:173], v[186:189], v[52:55]
	v_mfma_f32_16x16x32_bf16 v[48:51], v[178:181], v[186:189], v[48:51]
	v_mfma_f32_16x16x32_bf16 v[36:39], v[170:173], v[200:203], v[36:39]
	v_mfma_f32_16x16x32_bf16 v[32:35], v[178:181], v[200:203], v[32:35]
	v_mfma_f32_16x16x32_bf16 v[20:23], v[170:173], v[208:211], v[20:23]
	v_mfma_f32_16x16x32_bf16 v[16:19], v[178:181], v[208:211], v[16:19]
	v_mfma_f32_16x16x32_bf16 v[4:7], v[170:173], v[216:219], v[4:7]
	v_mfma_f32_16x16x32_bf16 v[0:3], v[178:181], v[216:219], v[0:3]
	s_setprio 0
	s_barrier
	s_add_i32 s59, 0, 0x18000
	s_add_i32 s60, 0, 0x1c000
	v_add_u32_e32 v162, s59, v149
	v_add_u32_e32 v178, s60, v149
	ds_read_b128 v[144:147], v162
	ds_read_b128 v[154:157], v162 offset:1024
	ds_read_b128 v[158:161], v162 offset:2048
	ds_read_b128 v[162:165], v162 offset:3072
	ds_read_b128 v[166:169], v178
	ds_read_b128 v[170:173], v178 offset:1024
	ds_read_b128 v[174:177], v178 offset:2048
	ds_read_b128 v[178:181], v178 offset:3072
	s_add_u32 s30, s30, 0x40000
	s_addc_u32 s31, s31, 0
	s_mov_b32 m0, s33
	v_lshl_add_u64 v[226:227], s[30:31], 0, v[128:129]
	ds_read_b128 v[182:185], v153 offset:32768
	ds_read_b128 v[186:189], v153 offset:33792
	ds_read_b128 v[190:193], v153 offset:34816
	ds_read_b128 v[200:203], v153 offset:35840
	ds_read_b128 v[204:207], v153 offset:36864
	ds_read_b128 v[208:211], v153 offset:37888
	ds_read_b128 v[212:215], v153 offset:38912
	ds_read_b128 v[216:219], v153 offset:39936
	global_load_lds_dwordx4 v[226:227], off
	v_lshl_add_u64 v[226:227], s[30:31], 0, v[132:133]
	s_mov_b32 m0, s36
	s_nop 0
	global_load_lds_dwordx4 v[226:227], off
	s_waitcnt vmcnt(8)
	s_waitcnt lgkmcnt(0)
	s_barrier
	s_setprio 1
	s_waitcnt lgkmcnt(0)
	v_mfma_f32_16x16x32_bf16 v[124:127], v[144:147], v[182:185], v[124:127]
	v_mfma_f32_16x16x32_bf16 v[120:123], v[158:161], v[182:185], v[120:123]
	v_mfma_f32_16x16x32_bf16 v[108:111], v[144:147], v[190:193], v[108:111]
	v_mfma_f32_16x16x32_bf16 v[104:107], v[158:161], v[190:193], v[104:107]
	v_mfma_f32_16x16x32_bf16 v[92:95], v[144:147], v[204:207], v[92:95]
	v_mfma_f32_16x16x32_bf16 v[88:91], v[158:161], v[204:207], v[88:91]
	v_mfma_f32_16x16x32_bf16 v[76:79], v[144:147], v[212:215], v[76:79]
	v_mfma_f32_16x16x32_bf16 v[72:75], v[158:161], v[212:215], v[72:75]
	v_mfma_f32_16x16x32_bf16 v[124:127], v[154:157], v[186:189], v[124:127]
	v_mfma_f32_16x16x32_bf16 v[120:123], v[162:165], v[186:189], v[120:123]
	v_mfma_f32_16x16x32_bf16 v[108:111], v[154:157], v[200:203], v[108:111]
	v_mfma_f32_16x16x32_bf16 v[104:107], v[162:165], v[200:203], v[104:107]
	v_mfma_f32_16x16x32_bf16 v[92:95], v[154:157], v[208:211], v[92:95]
	v_mfma_f32_16x16x32_bf16 v[88:91], v[162:165], v[208:211], v[88:91]
	v_mfma_f32_16x16x32_bf16 v[76:79], v[154:157], v[216:219], v[76:79]
	v_mfma_f32_16x16x32_bf16 v[72:75], v[162:165], v[216:219], v[72:75]
	v_mfma_f32_16x16x32_bf16 v[116:119], v[166:169], v[182:185], v[116:119]
	v_mfma_f32_16x16x32_bf16 v[112:115], v[174:177], v[182:185], v[112:115]
	v_mfma_f32_16x16x32_bf16 v[100:103], v[166:169], v[190:193], v[100:103]
	v_mfma_f32_16x16x32_bf16 v[96:99], v[174:177], v[190:193], v[96:99]
	v_mfma_f32_16x16x32_bf16 v[84:87], v[166:169], v[204:207], v[84:87]
	v_mfma_f32_16x16x32_bf16 v[80:83], v[174:177], v[204:207], v[80:83]
	v_mfma_f32_16x16x32_bf16 v[68:71], v[166:169], v[212:215], v[68:71]
	v_mfma_f32_16x16x32_bf16 v[64:67], v[174:177], v[212:215], v[64:67]
	v_mfma_f32_16x16x32_bf16 v[116:119], v[170:173], v[186:189], v[116:119]
	v_mfma_f32_16x16x32_bf16 v[112:115], v[178:181], v[186:189], v[112:115]
	v_mfma_f32_16x16x32_bf16 v[100:103], v[170:173], v[200:203], v[100:103]
	v_mfma_f32_16x16x32_bf16 v[96:99], v[178:181], v[200:203], v[96:99]
	v_mfma_f32_16x16x32_bf16 v[84:87], v[170:173], v[208:211], v[84:87]
	v_mfma_f32_16x16x32_bf16 v[80:83], v[178:181], v[208:211], v[80:83]
	v_mfma_f32_16x16x32_bf16 v[68:71], v[170:173], v[216:219], v[68:71]
	v_mfma_f32_16x16x32_bf16 v[64:67], v[178:181], v[216:219], v[64:67]
	s_setprio 0
	s_barrier
	s_add_i32 s30, s59, s3
	v_lshl_add_u64 v[196:197], v[196:197], 0, s[12:13]
	s_mov_b32 m0, s30
	ds_read_b128 v[182:185], v153 offset:49152
	ds_read_b128 v[186:189], v153 offset:50176
	ds_read_b128 v[190:193], v153 offset:51200
	ds_read_b128 v[200:203], v153 offset:52224
	ds_read_b128 v[204:207], v153 offset:53248
	ds_read_b128 v[208:211], v153 offset:54272
	ds_read_b128 v[212:215], v153 offset:55296
	ds_read_b128 v[216:219], v153 offset:56320
	global_load_lds_dwordx4 v[196:197], off
	s_add_i32 m0, s30, 0x2000
	s_add_u32 s8, s8, 0x40080
	v_lshl_add_u64 v[196:197], v[220:221], 0, s[12:13]
	s_addc_u32 s9, s9, 0
	s_add_i32 s30, s60, s3
	global_load_lds_dwordx4 v[196:197], off
	v_lshl_add_u64 v[196:197], s[8:9], 0, v[130:131]
	s_mov_b32 m0, s30
	s_nop 0
	global_load_lds_dwordx4 v[196:197], off
	v_lshl_add_u64 v[196:197], s[8:9], 0, v[134:135]
	s_add_i32 m0, s30, 0x2000
	s_nop 0
	global_load_lds_dwordx4 v[196:197], off
	v_lshl_add_u64 v[196:197], v[222:223], 0, s[12:13]
	s_mov_b32 m0, s38
	s_nop 0
	global_load_lds_dwordx4 v[196:197], off
	v_lshl_add_u64 v[196:197], v[224:225], 0, s[12:13]
	s_mov_b32 m0, s39
	s_nop 0
	global_load_lds_dwordx4 v[196:197], off
	s_waitcnt vmcnt(8)
	s_waitcnt lgkmcnt(0)
	s_barrier
	s_setprio 1
	s_waitcnt lgkmcnt(0)
	v_mfma_f32_16x16x32_bf16 v[60:63], v[144:147], v[182:185], v[60:63]
	v_mfma_f32_16x16x32_bf16 v[56:59], v[158:161], v[182:185], v[56:59]
	v_mfma_f32_16x16x32_bf16 v[44:47], v[144:147], v[190:193], v[44:47]
	v_mfma_f32_16x16x32_bf16 v[40:43], v[158:161], v[190:193], v[40:43]
	v_mfma_f32_16x16x32_bf16 v[28:31], v[144:147], v[204:207], v[28:31]
	v_mfma_f32_16x16x32_bf16 v[24:27], v[158:161], v[204:207], v[24:27]
	v_mfma_f32_16x16x32_bf16 v[12:15], v[144:147], v[212:215], v[12:15]
	v_mfma_f32_16x16x32_bf16 v[8:11], v[158:161], v[212:215], v[8:11]
	v_mfma_f32_16x16x32_bf16 v[60:63], v[154:157], v[186:189], v[60:63]
	v_mfma_f32_16x16x32_bf16 v[56:59], v[162:165], v[186:189], v[56:59]
	v_mfma_f32_16x16x32_bf16 v[44:47], v[154:157], v[200:203], v[44:47]
	v_mfma_f32_16x16x32_bf16 v[40:43], v[162:165], v[200:203], v[40:43]
	v_mfma_f32_16x16x32_bf16 v[28:31], v[154:157], v[208:211], v[28:31]
	v_mfma_f32_16x16x32_bf16 v[24:27], v[162:165], v[208:211], v[24:27]
	v_mfma_f32_16x16x32_bf16 v[12:15], v[154:157], v[216:219], v[12:15]
	v_mfma_f32_16x16x32_bf16 v[8:11], v[162:165], v[216:219], v[8:11]
	v_mfma_f32_16x16x32_bf16 v[52:55], v[166:169], v[182:185], v[52:55]
	v_mfma_f32_16x16x32_bf16 v[48:51], v[174:177], v[182:185], v[48:51]
	v_mfma_f32_16x16x32_bf16 v[36:39], v[166:169], v[190:193], v[36:39]
	v_mfma_f32_16x16x32_bf16 v[32:35], v[174:177], v[190:193], v[32:35]
	v_mfma_f32_16x16x32_bf16 v[20:23], v[166:169], v[204:207], v[20:23]
	v_mfma_f32_16x16x32_bf16 v[16:19], v[174:177], v[204:207], v[16:19]
	v_mfma_f32_16x16x32_bf16 v[4:7], v[166:169], v[212:215], v[4:7]
	v_mfma_f32_16x16x32_bf16 v[0:3], v[174:177], v[212:215], v[0:3]
	v_mfma_f32_16x16x32_bf16 v[52:55], v[170:173], v[186:189], v[52:55]
	v_mfma_f32_16x16x32_bf16 v[48:51], v[178:181], v[186:189], v[48:51]
	v_mfma_f32_16x16x32_bf16 v[36:39], v[170:173], v[200:203], v[36:39]
	v_mfma_f32_16x16x32_bf16 v[32:35], v[178:181], v[200:203], v[32:35]
	v_mfma_f32_16x16x32_bf16 v[20:23], v[170:173], v[208:211], v[20:23]
	v_mfma_f32_16x16x32_bf16 v[16:19], v[178:181], v[208:211], v[16:19]
	v_mfma_f32_16x16x32_bf16 v[4:7], v[170:173], v[216:219], v[4:7]
	v_mfma_f32_16x16x32_bf16 v[0:3], v[178:181], v[216:219], v[0:3]
	s_setprio 0
	s_barrier
	s_add_i32 s58, s58, 2
	s_add_u32 s28, s28, 0x100
	s_addc_u32 s29, s29, 0
	s_add_u32 s55, s55, 0x100
	s_addc_u32 s57, s57, 0
	s_cmp_gt_u32 s58, 13
	s_cbranch_scc0 .LBB0_1226
	s_and_b64 vcc, exec, s[14:15]
	s_cbranch_vccz .LBB0_1229
	s_barrier

.LBB0_1325:
	ds_read_b128 v[144:147], v154
	ds_read_b128 v[158:161], v154 offset:1024
	ds_read_b128 v[162:165], v154 offset:2048
	ds_read_b128 v[166:169], v154 offset:3072
	ds_read_b128 v[170:173], v155
	ds_read_b128 v[174:177], v155 offset:1024
	ds_read_b128 v[178:181], v155 offset:2048
	ds_read_b128 v[182:185], v155 offset:3072
	s_add_u32 s8, s24, 0xfffc0080
	s_addc_u32 s9, s25, -1
	s_cmp_eq_u32 s45, 12
	s_cselect_b32 s27, s15, s9
	s_cselect_b32 s26, s39, s8
	s_cselect_b32 s9, s13, s44
	s_cselect_b32 s8, s40, s41
	v_lshl_add_u64 v[148:149], s[24:25], 0, v[136:137]
	s_add_i32 m0, s4, 0xc000
	ds_read_b128 v[186:189], v156
	ds_read_b128 v[190:193], v156 offset:1024
	ds_read_b128 v[196:199], v156 offset:2048
	ds_read_b128 v[200:203], v156 offset:3072
	ds_read_b128 v[204:207], v156 offset:4096
	ds_read_b128 v[208:211], v156 offset:5120
	ds_read_b128 v[212:215], v156 offset:6144
	ds_read_b128 v[216:219], v156 offset:7168
	global_load_lds_dwordx4 v[148:149], off
	v_lshl_add_u64 v[148:149], s[24:25], 0, v[138:139]
	s_add_i32 m0, s4, 0xe000
	s_nop 0
	global_load_lds_dwordx4 v[148:149], off
	s_waitcnt vmcnt(8)
	s_waitcnt lgkmcnt(0)
	s_barrier
	s_setprio 1
	s_waitcnt lgkmcnt(0)
	v_mfma_f32_16x16x32_bf16 v[124:127], v[144:147], v[186:189], v[124:127]
	v_mfma_f32_16x16x32_bf16 v[120:123], v[162:165], v[186:189], v[120:123]
	v_mfma_f32_16x16x32_bf16 v[108:111], v[144:147], v[196:199], v[108:111]
	v_mfma_f32_16x16x32_bf16 v[104:107], v[162:165], v[196:199], v[104:107]
	v_mfma_f32_16x16x32_bf16 v[92:95], v[144:147], v[204:207], v[92:95]
	v_mfma_f32_16x16x32_bf16 v[88:91], v[162:165], v[204:207], v[88:91]
	v_mfma_f32_16x16x32_bf16 v[76:79], v[144:147], v[212:215], v[76:79]
	v_mfma_f32_16x16x32_bf16 v[72:75], v[162:165], v[212:215], v[72:75]
	v_mfma_f32_16x16x32_bf16 v[124:127], v[158:161], v[190:193], v[124:127]
	v_mfma_f32_16x16x32_bf16 v[120:123], v[166:169], v[190:193], v[120:123]
	v_mfma_f32_16x16x32_bf16 v[108:111], v[158:161], v[200:203], v[108:111]
	v_mfma_f32_16x16x32_bf16 v[104:107], v[166:169], v[200:203], v[104:107]
	v_mfma_f32_16x16x32_bf16 v[92:95], v[158:161], v[208:211], v[92:95]
	v_mfma_f32_16x16x32_bf16 v[88:91], v[166:169], v[208:211], v[88:91]
	v_mfma_f32_16x16x32_bf16 v[76:79], v[158:161], v[216:219], v[76:79]
	v_mfma_f32_16x16x32_bf16 v[72:75], v[166:169], v[216:219], v[72:75]
	v_mfma_f32_16x16x32_bf16 v[116:119], v[170:173], v[186:189], v[116:119]
	v_mfma_f32_16x16x32_bf16 v[112:115], v[178:181], v[186:189], v[112:115]
	v_mfma_f32_16x16x32_bf16 v[100:103], v[170:173], v[196:199], v[100:103]
	v_mfma_f32_16x16x32_bf16 v[96:99], v[178:181], v[196:199], v[96:99]
	v_mfma_f32_16x16x32_bf16 v[84:87], v[170:173], v[204:207], v[84:87]
	v_mfma_f32_16x16x32_bf16 v[80:83], v[178:181], v[204:207], v[80:83]
	v_mfma_f32_16x16x32_bf16 v[68:71], v[170:173], v[212:215], v[68:71]
	v_mfma_f32_16x16x32_bf16 v[64:67], v[178:181], v[212:215], v[64:67]
	v_mfma_f32_16x16x32_bf16 v[116:119], v[174:177], v[190:193], v[116:119]
	v_mfma_f32_16x16x32_bf16 v[112:115], v[182:185], v[190:193], v[112:115]
	v_mfma_f32_16x16x32_bf16 v[100:103], v[174:177], v[200:203], v[100:103]
	v_mfma_f32_16x16x32_bf16 v[96:99], v[182:185], v[200:203], v[96:99]
	v_mfma_f32_16x16x32_bf16 v[84:87], v[174:177], v[208:211], v[84:87]
	v_mfma_f32_16x16x32_bf16 v[80:83], v[182:185], v[208:211], v[80:83]
	v_mfma_f32_16x16x32_bf16 v[68:71], v[174:177], v[216:219], v[68:71]
	v_mfma_f32_16x16x32_bf16 v[64:67], v[182:185], v[216:219], v[64:67]
	s_setprio 0
	s_barrier
	s_add_i32 s46, s31, s3
	v_lshl_add_u64 v[148:149], s[8:9], 0, v[132:133]
	s_mov_b32 m0, s46
	ds_read_b128 v[186:189], v156 offset:16384
	ds_read_b128 v[190:193], v156 offset:17408
	ds_read_b128 v[196:199], v156 offset:18432
	ds_read_b128 v[200:203], v156 offset:19456
	ds_read_b128 v[204:207], v156 offset:20480
	ds_read_b128 v[208:211], v156 offset:21504
	ds_read_b128 v[212:215], v156 offset:22528
	ds_read_b128 v[216:219], v156 offset:23552
	global_load_lds_dwordx4 v[148:149], off
	s_add_i32 m0, s46, 0x2000
	s_add_u32 s46, s8, 0x40000
	v_lshl_add_u64 v[220:221], s[8:9], 0, v[128:129]
	s_addc_u32 s47, s9, 0
	s_add_i32 s50, s33, s3
	global_load_lds_dwordx4 v[220:221], off
	v_lshl_add_u64 v[222:223], s[46:47], 0, v[132:133]
	s_mov_b32 m0, s50
	v_lshl_add_u64 v[224:225], s[26:27], 0, v[130:131]
	global_load_lds_dwordx4 v[222:223], off
	v_lshl_add_u64 v[222:223], s[46:47], 0, v[128:129]
	s_add_i32 m0, s50, 0x2000
	s_nop 0
	global_load_lds_dwordx4 v[222:223], off
	v_lshl_add_u64 v[222:223], s[26:27], 0, v[134:135]
	s_mov_b32 m0, s4
	s_nop 0
	global_load_lds_dwordx4 v[222:223], off
	s_mov_b32 m0, s5
	s_nop 0
	global_load_lds_dwordx4 v[224:225], off
	s_waitcnt vmcnt(8)
	s_waitcnt lgkmcnt(0)
	s_barrier
	s_setprio 1
	s_waitcnt lgkmcnt(0)
	v_mfma_f32_16x16x32_bf16 v[60:63], v[144:147], v[186:189], v[60:63]
	v_mfma_f32_16x16x32_bf16 v[56:59], v[162:165], v[186:189], v[56:59]
	v_mfma_f32_16x16x32_bf16 v[44:47], v[144:147], v[196:199], v[44:47]
	v_mfma_f32_16x16x32_bf16 v[40:43], v[162:165], v[196:199], v[40:43]
	v_mfma_f32_16x16x32_bf16 v[28:31], v[144:147], v[204:207], v[28:31]
	v_mfma_f32_16x16x32_bf16 v[24:27], v[162:165], v[204:207], v[24:27]
	v_mfma_f32_16x16x32_bf16 v[12:15], v[144:147], v[212:215], v[12:15]
	v_mfma_f32_16x16x32_bf16 v[8:11], v[162:165], v[212:215], v[8:11]
	v_mfma_f32_16x16x32_bf16 v[60:63], v[158:161], v[190:193], v[60:63]
	v_mfma_f32_16x16x32_bf16 v[56:59], v[166:169], v[190:193], v[56:59]
	v_mfma_f32_16x16x32_bf16 v[44:47], v[158:161], v[200:203], v[44:47]
	v_mfma_f32_16x16x32_bf16 v[40:43], v[166:169], v[200:203], v[40:43]
	v_mfma_f32_16x16x32_bf16 v[28:31], v[158:161], v[208:211], v[28:31]
	v_mfma_f32_16x16x32_bf16 v[24:27], v[166:169], v[208:211], v[24:27]
	v_mfma_f32_16x16x32_bf16 v[12:15], v[158:161], v[216:219], v[12:15]
	v_mfma_f32_16x16x32_bf16 v[8:11], v[166:169], v[216:219], v[8:11]
	v_mfma_f32_16x16x32_bf16 v[52:55], v[170:173], v[186:189], v[52:55]
	v_mfma_f32_16x16x32_bf16 v[48:51], v[178:181], v[186:189], v[48:51]
	v_mfma_f32_16x16x32_bf16 v[36:39], v[170:173], v[196:199], v[36:39]
	v_mfma_f32_16x16x32_bf16 v[32:35], v[178:181], v[196:199], v[32:35]
	v_mfma_f32_16x16x32_bf16 v[20:23], v[170:173], v[204:207], v[20:23]
	v_mfma_f32_16x16x32_bf16 v[16:19], v[178:181], v[204:207], v[16:19]
	v_mfma_f32_16x16x32_bf16 v[4:7], v[170:173], v[212:215], v[4:7]
	v_mfma_f32_16x16x32_bf16 v[0:3], v[178:181], v[212:215], v[0:3]
	v_mfma_f32_16x16x32_bf16 v[52:55], v[174:177], v[190:193], v[52:55]
	v_mfma_f32_16x16x32_bf16 v[48:51], v[182:185], v[190:193], v[48:51]
	v_mfma_f32_16x16x32_bf16 v[36:39], v[174:177], v[200:203], v[36:39]
	v_mfma_f32_16x16x32_bf16 v[32:35], v[182:185], v[200:203], v[32:35]
	v_mfma_f32_16x16x32_bf16 v[20:23], v[174:177], v[208:211], v[20:23]
	v_mfma_f32_16x16x32_bf16 v[16:19], v[182:185], v[208:211], v[16:19]
	v_mfma_f32_16x16x32_bf16 v[4:7], v[174:177], v[216:219], v[4:7]
	v_mfma_f32_16x16x32_bf16 v[0:3], v[182:185], v[216:219], v[0:3]
	s_setprio 0
	s_barrier
	s_add_i32 s46, 0, 0x18000
	v_add_u32_e32 v157, s46, v151
	s_add_i32 s47, 0, 0x1c000
	ds_read_b128 v[144:147], v157
	ds_read_b128 v[158:161], v157 offset:1024
	ds_read_b128 v[162:165], v157 offset:2048
	ds_read_b128 v[166:169], v157 offset:3072
	v_add_u32_e32 v157, s47, v151
	ds_read_b128 v[170:173], v157
	ds_read_b128 v[174:177], v157 offset:1024
	ds_read_b128 v[178:181], v157 offset:2048
	ds_read_b128 v[182:185], v157 offset:3072
	s_add_u32 s26, s26, 0x40000
	s_addc_u32 s27, s27, 0
	s_mov_b32 m0, s23
	v_lshl_add_u64 v[226:227], s[26:27], 0, v[134:135]
	ds_read_b128 v[186:189], v156 offset:32768
	ds_read_b128 v[190:193], v156 offset:33792
	ds_read_b128 v[196:199], v156 offset:34816
	ds_read_b128 v[200:203], v156 offset:35840
	ds_read_b128 v[204:207], v156 offset:36864
	ds_read_b128 v[208:211], v156 offset:37888
	ds_read_b128 v[212:215], v156 offset:38912
	ds_read_b128 v[216:219], v156 offset:39936
	global_load_lds_dwordx4 v[226:227], off
	v_lshl_add_u64 v[226:227], s[26:27], 0, v[130:131]
	s_mov_b32 m0, s28
	s_nop 0
	global_load_lds_dwordx4 v[226:227], off
	s_waitcnt vmcnt(8)
	s_waitcnt lgkmcnt(0)
	s_barrier
	s_setprio 1
	s_waitcnt lgkmcnt(0)
	v_mfma_f32_16x16x32_bf16 v[124:127], v[144:147], v[186:189], v[124:127]
	v_mfma_f32_16x16x32_bf16 v[120:123], v[162:165], v[186:189], v[120:123]
	v_mfma_f32_16x16x32_bf16 v[108:111], v[144:147], v[196:199], v[108:111]
	v_mfma_f32_16x16x32_bf16 v[104:107], v[162:165], v[196:199], v[104:107]
	v_mfma_f32_16x16x32_bf16 v[92:95], v[144:147], v[204:207], v[92:95]
	v_mfma_f32_16x16x32_bf16 v[88:91], v[162:165], v[204:207], v[88:91]
	v_mfma_f32_16x16x32_bf16 v[76:79], v[144:147], v[212:215], v[76:79]
	v_mfma_f32_16x16x32_bf16 v[72:75], v[162:165], v[212:215], v[72:75]
	v_mfma_f32_16x16x32_bf16 v[124:127], v[158:161], v[190:193], v[124:127]
	v_mfma_f32_16x16x32_bf16 v[120:123], v[166:169], v[190:193], v[120:123]
	v_mfma_f32_16x16x32_bf16 v[108:111], v[158:161], v[200:203], v[108:111]
	v_mfma_f32_16x16x32_bf16 v[104:107], v[166:169], v[200:203], v[104:107]
	v_mfma_f32_16x16x32_bf16 v[92:95], v[158:161], v[208:211], v[92:95]
	v_mfma_f32_16x16x32_bf16 v[88:91], v[166:169], v[208:211], v[88:91]
	v_mfma_f32_16x16x32_bf16 v[76:79], v[158:161], v[216:219], v[76:79]
	v_mfma_f32_16x16x32_bf16 v[72:75], v[166:169], v[216:219], v[72:75]
	v_mfma_f32_16x16x32_bf16 v[116:119], v[170:173], v[186:189], v[116:119]
	v_mfma_f32_16x16x32_bf16 v[112:115], v[178:181], v[186:189], v[112:115]
	v_mfma_f32_16x16x32_bf16 v[100:103], v[170:173], v[196:199], v[100:103]
	v_mfma_f32_16x16x32_bf16 v[96:99], v[178:181], v[196:199], v[96:99]
	v_mfma_f32_16x16x32_bf16 v[84:87], v[170:173], v[204:207], v[84:87]
	v_mfma_f32_16x16x32_bf16 v[80:83], v[178:181], v[204:207], v[80:83]
	v_mfma_f32_16x16x32_bf16 v[68:71], v[170:173], v[212:215], v[68:71]
	v_mfma_f32_16x16x32_bf16 v[64:67], v[178:181], v[212:215], v[64:67]
	v_mfma_f32_16x16x32_bf16 v[116:119], v[174:177], v[190:193], v[116:119]
	v_mfma_f32_16x16x32_bf16 v[112:115], v[182:185], v[190:193], v[112:115]
	v_mfma_f32_16x16x32_bf16 v[100:103], v[174:177], v[200:203], v[100:103]
	v_mfma_f32_16x16x32_bf16 v[96:99], v[182:185], v[200:203], v[96:99]
	v_mfma_f32_16x16x32_bf16 v[84:87], v[174:177], v[208:211], v[84:87]
	v_mfma_f32_16x16x32_bf16 v[80:83], v[182:185], v[208:211], v[80:83]
	v_mfma_f32_16x16x32_bf16 v[68:71], v[174:177], v[216:219], v[68:71]
	v_mfma_f32_16x16x32_bf16 v[64:67], v[182:185], v[216:219], v[64:67]
	s_setprio 0
	s_barrier
	s_add_i32 s26, s46, s3
	v_lshl_add_u64 v[148:149], v[148:149], 0, s[6:7]
	s_mov_b32 m0, s26
	ds_read_b128 v[186:189], v156 offset:49152
	ds_read_b128 v[190:193], v156 offset:50176
	ds_read_b128 v[196:199], v156 offset:51200
	ds_read_b128 v[200:203], v156 offset:52224
	ds_read_b128 v[204:207], v156 offset:53248
	ds_read_b128 v[208:211], v156 offset:54272
	ds_read_b128 v[212:215], v156 offset:55296
	ds_read_b128 v[216:219], v156 offset:56320
	global_load_lds_dwordx4 v[148:149], off
	s_add_i32 m0, s26, 0x2000
	s_add_u32 s8, s8, 0x40080
	v_lshl_add_u64 v[148:149], v[220:221], 0, s[6:7]
	s_addc_u32 s9, s9, 0
	s_add_i32 s26, s47, s3
	global_load_lds_dwordx4 v[148:149], off
	v_lshl_add_u64 v[148:149], s[8:9], 0, v[132:133]
	s_mov_b32 m0, s26
	s_nop 0
	global_load_lds_dwordx4 v[148:149], off
	v_lshl_add_u64 v[148:149], s[8:9], 0, v[128:129]
	s_add_i32 m0, s26, 0x2000
	s_nop 0
	global_load_lds_dwordx4 v[148:149], off
	v_lshl_add_u64 v[148:149], v[222:223], 0, s[6:7]
	s_mov_b32 m0, s29
	s_nop 0
	global_load_lds_dwordx4 v[148:149], off
	v_lshl_add_u64 v[148:149], v[224:225], 0, s[6:7]
	s_mov_b32 m0, s30
	s_nop 0
	global_load_lds_dwordx4 v[148:149], off
	s_waitcnt vmcnt(8)
	s_waitcnt lgkmcnt(0)
	s_barrier
	s_setprio 1
	s_waitcnt lgkmcnt(0)
	v_mfma_f32_16x16x32_bf16 v[60:63], v[144:147], v[186:189], v[60:63]
	v_mfma_f32_16x16x32_bf16 v[56:59], v[162:165], v[186:189], v[56:59]
	v_mfma_f32_16x16x32_bf16 v[44:47], v[144:147], v[196:199], v[44:47]
	v_mfma_f32_16x16x32_bf16 v[40:43], v[162:165], v[196:199], v[40:43]
	v_mfma_f32_16x16x32_bf16 v[28:31], v[144:147], v[204:207], v[28:31]
	v_mfma_f32_16x16x32_bf16 v[24:27], v[162:165], v[204:207], v[24:27]
	v_mfma_f32_16x16x32_bf16 v[12:15], v[144:147], v[212:215], v[12:15]
	v_mfma_f32_16x16x32_bf16 v[8:11], v[162:165], v[212:215], v[8:11]
	v_mfma_f32_16x16x32_bf16 v[60:63], v[158:161], v[190:193], v[60:63]
	v_mfma_f32_16x16x32_bf16 v[56:59], v[166:169], v[190:193], v[56:59]
	v_mfma_f32_16x16x32_bf16 v[44:47], v[158:161], v[200:203], v[44:47]
	v_mfma_f32_16x16x32_bf16 v[40:43], v[166:169], v[200:203], v[40:43]
	v_mfma_f32_16x16x32_bf16 v[28:31], v[158:161], v[208:211], v[28:31]
	v_mfma_f32_16x16x32_bf16 v[24:27], v[166:169], v[208:211], v[24:27]
	v_mfma_f32_16x16x32_bf16 v[12:15], v[158:161], v[216:219], v[12:15]
	v_mfma_f32_16x16x32_bf16 v[8:11], v[166:169], v[216:219], v[8:11]
	v_mfma_f32_16x16x32_bf16 v[52:55], v[170:173], v[186:189], v[52:55]
	v_mfma_f32_16x16x32_bf16 v[48:51], v[178:181], v[186:189], v[48:51]
	v_mfma_f32_16x16x32_bf16 v[36:39], v[170:173], v[196:199], v[36:39]
	v_mfma_f32_16x16x32_bf16 v[32:35], v[178:181], v[196:199], v[32:35]
	v_mfma_f32_16x16x32_bf16 v[20:23], v[170:173], v[204:207], v[20:23]
	v_mfma_f32_16x16x32_bf16 v[16:19], v[178:181], v[204:207], v[16:19]
	v_mfma_f32_16x16x32_bf16 v[4:7], v[170:173], v[212:215], v[4:7]
	v_mfma_f32_16x16x32_bf16 v[0:3], v[178:181], v[212:215], v[0:3]
	v_mfma_f32_16x16x32_bf16 v[52:55], v[174:177], v[190:193], v[52:55]
	v_mfma_f32_16x16x32_bf16 v[48:51], v[182:185], v[190:193], v[48:51]
	v_mfma_f32_16x16x32_bf16 v[36:39], v[174:177], v[200:203], v[36:39]
	v_mfma_f32_16x16x32_bf16 v[32:35], v[182:185], v[200:203], v[32:35]
	v_mfma_f32_16x16x32_bf16 v[20:23], v[174:177], v[208:211], v[20:23]
	v_mfma_f32_16x16x32_bf16 v[16:19], v[182:185], v[208:211], v[16:19]
	v_mfma_f32_16x16x32_bf16 v[4:7], v[174:177], v[216:219], v[4:7]
	v_mfma_f32_16x16x32_bf16 v[0:3], v[182:185], v[216:219], v[0:3]
	s_setprio 0
	s_barrier
	s_add_i32 s45, s45, 2
	s_add_u32 s24, s24, 0x100
	s_addc_u32 s25, s25, 0
	s_add_u32 s41, s41, 0x100
	s_addc_u32 s44, s44, 0
	s_cmp_gt_u32 s45, 13
	s_cbranch_scc0 .LBB0_1325
	s_and_b64 vcc, exec, s[10:11]
	s_cbranch_vccz .LBB0_1328
	s_barrier

.LBB0_1399:
	ds_read_b128 v[144:147], v153
	ds_read_b128 v[156:159], v153 offset:1024
	ds_read_b128 v[160:163], v153 offset:2048
	ds_read_b128 v[164:167], v153 offset:3072
	ds_read_b128 v[168:171], v154
	ds_read_b128 v[172:175], v154 offset:1024
	ds_read_b128 v[176:179], v154 offset:2048
	ds_read_b128 v[180:183], v154 offset:3072
	s_add_u32 s36, s34, 0xfff00080
	s_addc_u32 s37, s35, -1
	s_cmp_eq_u32 s50, 60
	s_cselect_b32 s39, s25, s37
	s_cselect_b32 s38, s46, s36
	s_cselect_b32 s37, s23, s49
	s_cselect_b32 s36, s47, s48
	v_lshl_add_u64 v[148:149], s[34:35], 0, v[136:137]
	s_add_i32 m0, s4, 0xc000
	ds_read_b128 v[184:187], v155
	ds_read_b128 v[188:191], v155 offset:1024
	ds_read_b128 v[192:195], v155 offset:2048
	ds_read_b128 v[196:199], v155 offset:3072
	ds_read_b128 v[200:203], v155 offset:4096
	ds_read_b128 v[204:207], v155 offset:5120
	ds_read_b128 v[208:211], v155 offset:6144
	ds_read_b128 v[212:215], v155 offset:7168
	global_load_lds_dwordx4 v[148:149], off
	v_lshl_add_u64 v[148:149], s[34:35], 0, v[138:139]
	s_add_i32 m0, s4, 0xe000
	s_nop 0
	global_load_lds_dwordx4 v[148:149], off
	s_waitcnt vmcnt(8)
	s_waitcnt lgkmcnt(0)
	s_barrier
	s_setprio 1
	s_waitcnt lgkmcnt(0)
	v_mfma_f32_16x16x32_bf16 v[124:127], v[144:147], v[184:187], v[124:127]
	v_mfma_f32_16x16x32_bf16 v[120:123], v[160:163], v[184:187], v[120:123]
	v_mfma_f32_16x16x32_bf16 v[108:111], v[144:147], v[192:195], v[108:111]
	v_mfma_f32_16x16x32_bf16 v[104:107], v[160:163], v[192:195], v[104:107]
	v_mfma_f32_16x16x32_bf16 v[92:95], v[144:147], v[200:203], v[92:95]
	v_mfma_f32_16x16x32_bf16 v[88:91], v[160:163], v[200:203], v[88:91]
	v_mfma_f32_16x16x32_bf16 v[76:79], v[144:147], v[208:211], v[76:79]
	v_mfma_f32_16x16x32_bf16 v[72:75], v[160:163], v[208:211], v[72:75]
	v_mfma_f32_16x16x32_bf16 v[124:127], v[156:159], v[188:191], v[124:127]
	v_mfma_f32_16x16x32_bf16 v[120:123], v[164:167], v[188:191], v[120:123]
	v_mfma_f32_16x16x32_bf16 v[108:111], v[156:159], v[196:199], v[108:111]
	v_mfma_f32_16x16x32_bf16 v[104:107], v[164:167], v[196:199], v[104:107]
	v_mfma_f32_16x16x32_bf16 v[92:95], v[156:159], v[204:207], v[92:95]
	v_mfma_f32_16x16x32_bf16 v[88:91], v[164:167], v[204:207], v[88:91]
	v_mfma_f32_16x16x32_bf16 v[76:79], v[156:159], v[212:215], v[76:79]
	v_mfma_f32_16x16x32_bf16 v[72:75], v[164:167], v[212:215], v[72:75]
	v_mfma_f32_16x16x32_bf16 v[116:119], v[168:171], v[184:187], v[116:119]
	v_mfma_f32_16x16x32_bf16 v[112:115], v[176:179], v[184:187], v[112:115]
	v_mfma_f32_16x16x32_bf16 v[100:103], v[168:171], v[192:195], v[100:103]
	v_mfma_f32_16x16x32_bf16 v[96:99], v[176:179], v[192:195], v[96:99]
	v_mfma_f32_16x16x32_bf16 v[84:87], v[168:171], v[200:203], v[84:87]
	v_mfma_f32_16x16x32_bf16 v[80:83], v[176:179], v[200:203], v[80:83]
	v_mfma_f32_16x16x32_bf16 v[68:71], v[168:171], v[208:211], v[68:71]
	v_mfma_f32_16x16x32_bf16 v[64:67], v[176:179], v[208:211], v[64:67]
	v_mfma_f32_16x16x32_bf16 v[116:119], v[172:175], v[188:191], v[116:119]
	v_mfma_f32_16x16x32_bf16 v[112:115], v[180:183], v[188:191], v[112:115]
	v_mfma_f32_16x16x32_bf16 v[100:103], v[172:175], v[196:199], v[100:103]
	v_mfma_f32_16x16x32_bf16 v[96:99], v[180:183], v[196:199], v[96:99]
	v_mfma_f32_16x16x32_bf16 v[84:87], v[172:175], v[204:207], v[84:87]
	v_mfma_f32_16x16x32_bf16 v[80:83], v[180:183], v[204:207], v[80:83]
	v_mfma_f32_16x16x32_bf16 v[68:71], v[172:175], v[212:215], v[68:71]
	v_mfma_f32_16x16x32_bf16 v[64:67], v[180:183], v[212:215], v[64:67]
	s_setprio 0
	s_barrier
	s_add_i32 s51, s43, s3
	v_lshl_add_u64 v[148:149], s[36:37], 0, v[132:133]
	s_mov_b32 m0, s51
	ds_read_b128 v[184:187], v155 offset:16384
	ds_read_b128 v[188:191], v155 offset:17408
	ds_read_b128 v[192:195], v155 offset:18432
	ds_read_b128 v[196:199], v155 offset:19456
	ds_read_b128 v[200:203], v155 offset:20480
	ds_read_b128 v[204:207], v155 offset:21504
	ds_read_b128 v[208:211], v155 offset:22528
	ds_read_b128 v[212:215], v155 offset:23552
	global_load_lds_dwordx4 v[148:149], off
	s_add_i32 m0, s51, 0x2000
	s_add_u32 s52, s36, 0x100000
	v_lshl_add_u64 v[216:217], s[36:37], 0, v[128:129]
	s_addc_u32 s53, s37, 0
	s_add_i32 s51, s44, s3
	global_load_lds_dwordx4 v[216:217], off
	v_lshl_add_u64 v[218:219], s[52:53], 0, v[132:133]
	s_mov_b32 m0, s51
	v_lshl_add_u64 v[220:221], s[38:39], 0, v[130:131]
	global_load_lds_dwordx4 v[218:219], off
	v_lshl_add_u64 v[218:219], s[52:53], 0, v[128:129]
	s_add_i32 m0, s51, 0x2000
	s_nop 0
	global_load_lds_dwordx4 v[218:219], off
	v_lshl_add_u64 v[218:219], s[38:39], 0, v[134:135]
	s_mov_b32 m0, s4
	s_nop 0
	global_load_lds_dwordx4 v[218:219], off
	s_mov_b32 m0, s5
	s_nop 0
	global_load_lds_dwordx4 v[220:221], off
	s_waitcnt vmcnt(8)
	s_waitcnt lgkmcnt(0)
	s_barrier
	s_setprio 1
	s_waitcnt lgkmcnt(0)
	v_mfma_f32_16x16x32_bf16 v[60:63], v[144:147], v[184:187], v[60:63]
	v_mfma_f32_16x16x32_bf16 v[56:59], v[160:163], v[184:187], v[56:59]
	v_mfma_f32_16x16x32_bf16 v[44:47], v[144:147], v[192:195], v[44:47]
	v_mfma_f32_16x16x32_bf16 v[40:43], v[160:163], v[192:195], v[40:43]
	v_mfma_f32_16x16x32_bf16 v[28:31], v[144:147], v[200:203], v[28:31]
	v_mfma_f32_16x16x32_bf16 v[24:27], v[160:163], v[200:203], v[24:27]
	v_mfma_f32_16x16x32_bf16 v[12:15], v[144:147], v[208:211], v[12:15]
	v_mfma_f32_16x16x32_bf16 v[8:11], v[160:163], v[208:211], v[8:11]
	v_mfma_f32_16x16x32_bf16 v[60:63], v[156:159], v[188:191], v[60:63]
	v_mfma_f32_16x16x32_bf16 v[56:59], v[164:167], v[188:191], v[56:59]
	v_mfma_f32_16x16x32_bf16 v[44:47], v[156:159], v[196:199], v[44:47]
	v_mfma_f32_16x16x32_bf16 v[40:43], v[164:167], v[196:199], v[40:43]
	v_mfma_f32_16x16x32_bf16 v[28:31], v[156:159], v[204:207], v[28:31]
	v_mfma_f32_16x16x32_bf16 v[24:27], v[164:167], v[204:207], v[24:27]
	v_mfma_f32_16x16x32_bf16 v[12:15], v[156:159], v[212:215], v[12:15]
	v_mfma_f32_16x16x32_bf16 v[8:11], v[164:167], v[212:215], v[8:11]
	v_mfma_f32_16x16x32_bf16 v[52:55], v[168:171], v[184:187], v[52:55]
	v_mfma_f32_16x16x32_bf16 v[48:51], v[176:179], v[184:187], v[48:51]
	v_mfma_f32_16x16x32_bf16 v[36:39], v[168:171], v[192:195], v[36:39]
	v_mfma_f32_16x16x32_bf16 v[32:35], v[176:179], v[192:195], v[32:35]
	v_mfma_f32_16x16x32_bf16 v[20:23], v[168:171], v[200:203], v[20:23]
	v_mfma_f32_16x16x32_bf16 v[16:19], v[176:179], v[200:203], v[16:19]
	v_mfma_f32_16x16x32_bf16 v[4:7], v[168:171], v[208:211], v[4:7]
	v_mfma_f32_16x16x32_bf16 v[0:3], v[176:179], v[208:211], v[0:3]
	v_mfma_f32_16x16x32_bf16 v[52:55], v[172:175], v[188:191], v[52:55]
	v_mfma_f32_16x16x32_bf16 v[48:51], v[180:183], v[188:191], v[48:51]
	v_mfma_f32_16x16x32_bf16 v[36:39], v[172:175], v[196:199], v[36:39]
	v_mfma_f32_16x16x32_bf16 v[32:35], v[180:183], v[196:199], v[32:35]
	v_mfma_f32_16x16x32_bf16 v[20:23], v[172:175], v[204:207], v[20:23]
	v_mfma_f32_16x16x32_bf16 v[16:19], v[180:183], v[204:207], v[16:19]
	v_mfma_f32_16x16x32_bf16 v[4:7], v[172:175], v[212:215], v[4:7]
	v_mfma_f32_16x16x32_bf16 v[0:3], v[180:183], v[212:215], v[0:3]
	s_setprio 0
	s_barrier
	s_add_i32 s51, 0, 0x18000
	s_add_i32 s52, 0, 0x1c000
	v_add_u32_e32 v164, s51, v151
	v_add_u32_e32 v180, s52, v151
	ds_read_b128 v[144:147], v164
	ds_read_b128 v[156:159], v164 offset:1024
	ds_read_b128 v[160:163], v164 offset:2048
	ds_read_b128 v[164:167], v164 offset:3072
	ds_read_b128 v[168:171], v180
	ds_read_b128 v[172:175], v180 offset:1024
	ds_read_b128 v[176:179], v180 offset:2048
	ds_read_b128 v[180:183], v180 offset:3072
	s_add_u32 s38, s38, 0x100000
	s_addc_u32 s39, s39, 0
	s_mov_b32 m0, s31
	v_lshl_add_u64 v[222:223], s[38:39], 0, v[134:135]
	ds_read_b128 v[184:187], v155 offset:32768
	ds_read_b128 v[188:191], v155 offset:33792
	ds_read_b128 v[192:195], v155 offset:34816
	ds_read_b128 v[196:199], v155 offset:35840
	ds_read_b128 v[200:203], v155 offset:36864
	ds_read_b128 v[204:207], v155 offset:37888
	ds_read_b128 v[208:211], v155 offset:38912
	ds_read_b128 v[212:215], v155 offset:39936
	global_load_lds_dwordx4 v[222:223], off
	v_lshl_add_u64 v[222:223], s[38:39], 0, v[130:131]
	s_mov_b32 m0, s33
	s_nop 0
	global_load_lds_dwordx4 v[222:223], off
	s_waitcnt vmcnt(8)
	s_waitcnt lgkmcnt(0)
	s_barrier
	s_setprio 1
	s_waitcnt lgkmcnt(0)
	v_mfma_f32_16x16x32_bf16 v[124:127], v[144:147], v[184:187], v[124:127]
	v_mfma_f32_16x16x32_bf16 v[120:123], v[160:163], v[184:187], v[120:123]
	v_mfma_f32_16x16x32_bf16 v[108:111], v[144:147], v[192:195], v[108:111]
	v_mfma_f32_16x16x32_bf16 v[104:107], v[160:163], v[192:195], v[104:107]
	v_mfma_f32_16x16x32_bf16 v[92:95], v[144:147], v[200:203], v[92:95]
	v_mfma_f32_16x16x32_bf16 v[88:91], v[160:163], v[200:203], v[88:91]
	v_mfma_f32_16x16x32_bf16 v[76:79], v[144:147], v[208:211], v[76:79]
	v_mfma_f32_16x16x32_bf16 v[72:75], v[160:163], v[208:211], v[72:75]
	v_mfma_f32_16x16x32_bf16 v[124:127], v[156:159], v[188:191], v[124:127]
	v_mfma_f32_16x16x32_bf16 v[120:123], v[164:167], v[188:191], v[120:123]
	v_mfma_f32_16x16x32_bf16 v[108:111], v[156:159], v[196:199], v[108:111]
	v_mfma_f32_16x16x32_bf16 v[104:107], v[164:167], v[196:199], v[104:107]
	v_mfma_f32_16x16x32_bf16 v[92:95], v[156:159], v[204:207], v[92:95]
	v_mfma_f32_16x16x32_bf16 v[88:91], v[164:167], v[204:207], v[88:91]
	v_mfma_f32_16x16x32_bf16 v[76:79], v[156:159], v[212:215], v[76:79]
	v_mfma_f32_16x16x32_bf16 v[72:75], v[164:167], v[212:215], v[72:75]
	v_mfma_f32_16x16x32_bf16 v[116:119], v[168:171], v[184:187], v[116:119]
	v_mfma_f32_16x16x32_bf16 v[112:115], v[176:179], v[184:187], v[112:115]
	v_mfma_f32_16x16x32_bf16 v[100:103], v[168:171], v[192:195], v[100:103]
	v_mfma_f32_16x16x32_bf16 v[96:99], v[176:179], v[192:195], v[96:99]
	v_mfma_f32_16x16x32_bf16 v[84:87], v[168:171], v[200:203], v[84:87]
	v_mfma_f32_16x16x32_bf16 v[80:83], v[176:179], v[200:203], v[80:83]
	v_mfma_f32_16x16x32_bf16 v[68:71], v[168:171], v[208:211], v[68:71]
	v_mfma_f32_16x16x32_bf16 v[64:67], v[176:179], v[208:211], v[64:67]
	v_mfma_f32_16x16x32_bf16 v[116:119], v[172:175], v[188:191], v[116:119]
	v_mfma_f32_16x16x32_bf16 v[112:115], v[180:183], v[188:191], v[112:115]
	v_mfma_f32_16x16x32_bf16 v[100:103], v[172:175], v[196:199], v[100:103]
	v_mfma_f32_16x16x32_bf16 v[96:99], v[180:183], v[196:199], v[96:99]
	v_mfma_f32_16x16x32_bf16 v[84:87], v[172:175], v[204:207], v[84:87]
	v_mfma_f32_16x16x32_bf16 v[80:83], v[180:183], v[204:207], v[80:83]
	v_mfma_f32_16x16x32_bf16 v[68:71], v[172:175], v[212:215], v[68:71]
	v_mfma_f32_16x16x32_bf16 v[64:67], v[180:183], v[212:215], v[64:67]
	s_setprio 0
	s_barrier
	s_add_i32 s38, s51, s3
	v_lshl_add_u64 v[148:149], v[148:149], 0, s[8:9]
	s_mov_b32 m0, s38
	ds_read_b128 v[184:187], v155 offset:49152
	ds_read_b128 v[188:191], v155 offset:50176
	ds_read_b128 v[192:195], v155 offset:51200
	ds_read_b128 v[196:199], v155 offset:52224
	ds_read_b128 v[200:203], v155 offset:53248
	ds_read_b128 v[204:207], v155 offset:54272
	ds_read_b128 v[208:211], v155 offset:55296
	ds_read_b128 v[212:215], v155 offset:56320
	global_load_lds_dwordx4 v[148:149], off
	s_add_i32 m0, s38, 0x2000
	s_add_u32 s36, s36, 0x100080
	v_lshl_add_u64 v[148:149], v[216:217], 0, s[8:9]
	s_addc_u32 s37, s37, 0
	s_add_i32 s38, s52, s3
	global_load_lds_dwordx4 v[148:149], off
	v_lshl_add_u64 v[148:149], s[36:37], 0, v[132:133]
	s_mov_b32 m0, s38
	s_nop 0
	global_load_lds_dwordx4 v[148:149], off
	v_lshl_add_u64 v[148:149], s[36:37], 0, v[128:129]
	s_add_i32 m0, s38, 0x2000
	s_nop 0
	global_load_lds_dwordx4 v[148:149], off
	v_lshl_add_u64 v[148:149], v[218:219], 0, s[8:9]
	s_mov_b32 m0, s41
	s_nop 0
	global_load_lds_dwordx4 v[148:149], off
	v_lshl_add_u64 v[148:149], v[220:221], 0, s[8:9]
	s_mov_b32 m0, s42
	s_nop 0
	global_load_lds_dwordx4 v[148:149], off
	s_waitcnt vmcnt(8)
	s_waitcnt lgkmcnt(0)
	s_barrier
	s_setprio 1
	s_waitcnt lgkmcnt(0)
	v_mfma_f32_16x16x32_bf16 v[60:63], v[144:147], v[184:187], v[60:63]
	v_mfma_f32_16x16x32_bf16 v[56:59], v[160:163], v[184:187], v[56:59]
	v_mfma_f32_16x16x32_bf16 v[44:47], v[144:147], v[192:195], v[44:47]
	v_mfma_f32_16x16x32_bf16 v[40:43], v[160:163], v[192:195], v[40:43]
	v_mfma_f32_16x16x32_bf16 v[28:31], v[144:147], v[200:203], v[28:31]
	v_mfma_f32_16x16x32_bf16 v[24:27], v[160:163], v[200:203], v[24:27]
	v_mfma_f32_16x16x32_bf16 v[12:15], v[144:147], v[208:211], v[12:15]
	v_mfma_f32_16x16x32_bf16 v[8:11], v[160:163], v[208:211], v[8:11]
	v_mfma_f32_16x16x32_bf16 v[60:63], v[156:159], v[188:191], v[60:63]
	v_mfma_f32_16x16x32_bf16 v[56:59], v[164:167], v[188:191], v[56:59]
	v_mfma_f32_16x16x32_bf16 v[44:47], v[156:159], v[196:199], v[44:47]
	v_mfma_f32_16x16x32_bf16 v[40:43], v[164:167], v[196:199], v[40:43]
	v_mfma_f32_16x16x32_bf16 v[28:31], v[156:159], v[204:207], v[28:31]
	v_mfma_f32_16x16x32_bf16 v[24:27], v[164:167], v[204:207], v[24:27]
	v_mfma_f32_16x16x32_bf16 v[12:15], v[156:159], v[212:215], v[12:15]
	v_mfma_f32_16x16x32_bf16 v[8:11], v[164:167], v[212:215], v[8:11]
	v_mfma_f32_16x16x32_bf16 v[52:55], v[168:171], v[184:187], v[52:55]
	v_mfma_f32_16x16x32_bf16 v[48:51], v[176:179], v[184:187], v[48:51]
	v_mfma_f32_16x16x32_bf16 v[36:39], v[168:171], v[192:195], v[36:39]
	v_mfma_f32_16x16x32_bf16 v[32:35], v[176:179], v[192:195], v[32:35]
	v_mfma_f32_16x16x32_bf16 v[20:23], v[168:171], v[200:203], v[20:23]
	v_mfma_f32_16x16x32_bf16 v[16:19], v[176:179], v[200:203], v[16:19]
	v_mfma_f32_16x16x32_bf16 v[4:7], v[168:171], v[208:211], v[4:7]
	v_mfma_f32_16x16x32_bf16 v[0:3], v[176:179], v[208:211], v[0:3]
	v_mfma_f32_16x16x32_bf16 v[52:55], v[172:175], v[188:191], v[52:55]
	v_mfma_f32_16x16x32_bf16 v[48:51], v[180:183], v[188:191], v[48:51]
	v_mfma_f32_16x16x32_bf16 v[36:39], v[172:175], v[196:199], v[36:39]
	v_mfma_f32_16x16x32_bf16 v[32:35], v[180:183], v[196:199], v[32:35]
	v_mfma_f32_16x16x32_bf16 v[20:23], v[172:175], v[204:207], v[20:23]
	v_mfma_f32_16x16x32_bf16 v[16:19], v[180:183], v[204:207], v[16:19]
	v_mfma_f32_16x16x32_bf16 v[4:7], v[172:175], v[212:215], v[4:7]
	v_mfma_f32_16x16x32_bf16 v[0:3], v[180:183], v[212:215], v[0:3]
	s_setprio 0
	s_barrier
	s_add_i32 s50, s50, 2
	s_add_u32 s34, s34, 0x100
	s_addc_u32 s35, s35, 0
	s_add_u32 s48, s48, 0x100
	s_addc_u32 s49, s49, 0
	s_cmp_gt_u32 s50, 61
	s_cbranch_scc0 .LBB0_1399
	s_and_b64 vcc, exec, s[10:11]
	s_cbranch_vccz .LBB0_1402
	s_barrier
